# V^T buffers stored in a fragment-contiguous tiled layout [d/64][tok/32][d/32&1][tok/16&1][d&31][tok/8&1][8 tok] by the transposed GEMM epilogue; SB and NSA V loads read that layout (SB V loads: 1KB co
# speedup vs baseline: 1.0176x; 1.0034x over previous
.LBB0_65:
	s_and_b64 vcc, exec, s[4:5]
	s_cbranch_vccz .LBB0_147
	s_cmp_eq_u32 s2, 4
	s_mov_b64 s[0:1], -1
	s_cbranch_scc0 .LBB0_147
	s_add_u32 s0, s80, 0xc400000
	s_addc_u32 s1, s81, 0
	v_writelane_b32 v254, s0, 10
	s_nop 1
	v_writelane_b32 v254, s1, 11
	s_mov_b64 s[0:1], -1
	v_readlane_b32 s4, v254, 3
	v_readlane_b32 s5, v254, 4
	s_and_b64 vcc, exec, s[4:5]
	s_cbranch_vccz .LBB0_135
	v_readlane_b32 s4, v253, 38
	v_and_b32_e32 v0, 63, v215
	v_readlane_b32 s12, v253, 46
	v_mov_b32 v1, s12
	v_readlane_b32 s13, v253, 47
	v_readfirstlane_b32 s0, v1
	v_mov_b32 v1, s13
	v_lshlrev_b32_e32 v160, 2, v0
	v_readfirstlane_b32 s1, v1
	v_xor_b32_e32 v5, 32, v205
	v_xor_b32_e32 v6, 16, v205
	v_xor_b32_e32 v7, 8, v205
	v_xor_b32_e32 v8, 4, v205
	v_xor_b32_e32 v9, 2, v205
	global_load_dword v1, v160, s[0:1]
	v_mov_b32 v2, s12
	v_xor_b32_e32 v10, 1, v205
	v_readfirstlane_b32 s0, v2
	v_mov_b32 v2, s13
	v_writelane_b32 v254, s22, 12
	v_readfirstlane_b32 s1, v2
	s_cmpk_gt_i32 s79, 0x3ff
	v_writelane_b32 v254, s23, 13
	v_lshl_add_u64 v[2:3], s[0:1], 0, v[160:161]
	flat_load_dword v4, v[2:3] offset:256
	v_mov_b32 v2, s12
	v_writelane_b32 v254, s29, 14
	v_readfirstlane_b32 s0, v2
	v_mov_b32 v2, s13
	v_writelane_b32 v254, s24, 16
	v_readfirstlane_b32 s1, v2
	v_readlane_b32 s5, v253, 39
	v_writelane_b32 v254, s25, 17
	v_lshl_add_u64 v[2:3], s[0:1], 0, v[160:161]
	flat_load_dword v2, v[2:3] offset:512
	v_and_b32_e32 v3, 64, v205
	v_add_u32_e32 v3, 64, v3
	v_cmp_lt_i32_e32 vcc, v5, v3
	v_writelane_b32 v254, s26, 18
	v_readlane_b32 s6, v253, 40
	v_cndmask_b32_e32 v5, v205, v5, vcc
	v_cmp_lt_i32_e32 vcc, v6, v3
	v_lshlrev_b32_e32 v97, 2, v5
	v_writelane_b32 v254, s27, 19
	v_cndmask_b32_e32 v6, v205, v6, vcc
	v_cmp_lt_i32_e32 vcc, v7, v3
	v_lshlrev_b32_e32 v99, 2, v6
	v_writelane_b32 v254, s84, 20
	v_cndmask_b32_e32 v7, v205, v7, vcc
	v_cmp_lt_i32_e32 vcc, v8, v3
	v_lshlrev_b32_e32 v101, 2, v7
	v_writelane_b32 v254, s85, 21
	v_cndmask_b32_e32 v8, v205, v8, vcc
	v_cmp_lt_i32_e32 vcc, v9, v3
	v_lshlrev_b32_e32 v103, 2, v8
	v_writelane_b32 v254, s76, 22
	v_cndmask_b32_e32 v9, v205, v9, vcc
	v_cmp_lt_i32_e32 vcc, v10, v3
	v_lshlrev_b32_e32 v158, 2, v9
	v_writelane_b32 v254, s77, 23
	v_cndmask_b32_e32 v3, v205, v10, vcc
	v_lshlrev_b32_e32 v159, 2, v3
	v_readlane_b32 s7, v253, 41
	v_readlane_b32 s8, v253, 42
	v_readlane_b32 s9, v253, 43
	v_readlane_b32 s10, v253, 44
	v_readlane_b32 s11, v253, 45
	v_readlane_b32 s14, v253, 48
	v_readlane_b32 s15, v253, 49
	v_readlane_b32 s16, v253, 50
	v_readlane_b32 s17, v253, 51
	v_readlane_b32 s18, v253, 52
	v_readlane_b32 s19, v253, 53
	s_waitcnt vmcnt(0)
	v_and_b32_e32 v3, 0x7fffffff, v1
	ds_bpermute_b32 v3, v97, v3
	v_max_f32_e64 v1, |v1|, |v1|
	s_waitcnt lgkmcnt(0)
	v_max_f32_e32 v3, v3, v3
	v_max_f32_e32 v1, v1, v3
	v_and_b32_e32 v5, 0x7fffffff, v4
	ds_bpermute_b32 v5, v97, v5
	v_max_f32_e64 v4, |v4|, |v4|
	s_waitcnt lgkmcnt(0)
	v_max_f32_e32 v5, v5, v5
	v_max_f32_e32 v4, v4, v5
	ds_bpermute_b32 v5, v99, v4
	v_and_b32_e32 v6, 0x7fffffff, v2
	ds_bpermute_b32 v3, v97, v6
	v_max_f32_e64 v2, |v2|, |v2|
	ds_bpermute_b32 v6, v99, v1
	s_waitcnt lgkmcnt(2)
	v_max_f32_e32 v5, v5, v5
	v_max_f32_e32 v4, v4, v5
	s_waitcnt lgkmcnt(1)
	v_max_f32_e32 v3, v3, v3
	v_max_f32_e32 v2, v2, v3
	ds_bpermute_b32 v3, v99, v2
	s_waitcnt lgkmcnt(1)
	v_max_f32_e32 v6, v6, v6
	v_max_f32_e32 v1, v1, v6
	ds_bpermute_b32 v5, v101, v4
	ds_bpermute_b32 v6, v101, v1
	s_waitcnt lgkmcnt(2)
	v_max_f32_e32 v3, v3, v3
	v_max_f32_e32 v2, v2, v3
	ds_bpermute_b32 v3, v101, v2
	s_waitcnt lgkmcnt(2)
	v_max_f32_e32 v5, v5, v5
	s_waitcnt lgkmcnt(1)
	v_max_f32_e32 v6, v6, v6
	v_max_f32_e32 v4, v4, v5
	v_max_f32_e32 v1, v1, v6
	s_waitcnt lgkmcnt(0)
	v_max_f32_e32 v3, v3, v3
	ds_bpermute_b32 v5, v103, v4
	v_max_f32_e32 v2, v2, v3
	ds_bpermute_b32 v6, v103, v1
	ds_bpermute_b32 v3, v103, v2
	s_waitcnt lgkmcnt(2)
	v_max_f32_e32 v5, v5, v5
	v_max_f32_e32 v4, v4, v5
	s_waitcnt lgkmcnt(1)
	v_max_f32_e32 v6, v6, v6
	s_waitcnt lgkmcnt(0)
	v_max_f32_e32 v3, v3, v3
	v_max_f32_e32 v1, v1, v6
	ds_bpermute_b32 v5, v158, v4
	v_max_f32_e32 v3, v2, v3
	ds_bpermute_b32 v6, v158, v1
	ds_bpermute_b32 v7, v158, v3
	s_waitcnt lgkmcnt(2)
	v_max_f32_e32 v5, v5, v5
	v_max_f32_e32 v4, v4, v5
	s_waitcnt lgkmcnt(1)
	v_max_f32_e32 v6, v6, v6
	s_waitcnt lgkmcnt(0)
	v_max_f32_e32 v5, v7, v7
	v_max_f32_e32 v1, v1, v6
	v_max_f32_e32 v3, v3, v5
	ds_bpermute_b32 v2, v159, v1
	ds_bpermute_b32 v6, v159, v4
	ds_bpermute_b32 v5, v159, v3
	s_cbranch_scc1 .LBB0_134
	s_add_u32 s0, s80, 0x9200000
	v_writelane_b32 v254, s0, 24
	s_addc_u32 s0, s81, 0
	v_writelane_b32 v254, s0, 25
	s_add_u32 s0, s80, 0x12400000
	s_addc_u32 s1, s81, 0
	v_writelane_b32 v254, s0, 27
	v_ashrrev_i32_e32 v7, 6, v162
	s_waitcnt lgkmcnt(2)
	v_max_f32_e32 v2, v2, v2
	v_writelane_b32 v254, s1, 28
	s_add_u32 s0, s80, 0xb200000
	v_writelane_b32 v254, s0, 29
	s_addc_u32 s0, s81, 0
	v_max_f32_e32 v1, v1, v1
	v_writelane_b32 v254, s0, 31
	v_lshrrev_b32_e32 v168, 5, v0
	s_movk_i32 s0, 0xfc20
	v_and_b32_e32 v8, 31, v215
	v_max_f32_e32 v167, v1, v2
	v_mul_lo_u32 v1, v7, s0
	v_readlane_b32 s0, v254, 14
	v_lshlrev_b32_e32 v170, 4, v168
	s_lshl_b32 s92, s0, 6
	v_add_u32_e32 v171, 0, v170
	v_mul_u32_u24_e32 v174, 0x90, v8
	s_mov_b32 s0, 0xd000
	s_waitcnt lgkmcnt(1)
	v_max_f32_e32 v6, v6, v6
	v_max_f32_e32 v4, v4, v4
	v_lshlrev_b32_e32 v98, 3, v168
	v_add3_u32 v176, v171, v174, s0
	v_readlane_b32 s0, v253, 10
	v_max_f32_e32 v164, v4, v6
	s_waitcnt lgkmcnt(0)
	v_max_f32_e32 v4, v5, v5
	v_add_u32_e32 v5, s0, v98
	v_readlane_b32 s0, v253, 11
	v_lshlrev_b32_e32 v9, 10, v7
	v_bfe_u32 v2, v215, 2, 3
	v_add_u32_e32 v6, s0, v98
	v_readlane_b32 s0, v253, 12
	v_add_u32_e32 v10, 0, v9
	v_lshl_or_b32 v169, v7, 3, v2
	v_add_u32_e32 v11, s0, v98
	v_readlane_b32 s0, v253, 13
	v_lshlrev_b32_e32 v102, 2, v168
	v_lshlrev_b32_e32 v2, 7, v2
	v_add_u32_e32 v12, s0, v98
	v_readlane_b32 s0, v253, 14
	v_max_f32_e32 v3, v3, v3
	v_add3_u32 v177, v10, v2, v102
	v_add_u32_e32 v13, s0, v98
	v_readlane_b32 s0, v253, 15
	v_lshlrev_b32_e32 v2, 4, v215
	v_max_f32_e32 v166, v3, v4
	v_add_u32_e32 v14, s0, v98
	v_readlane_b32 s0, v253, 16
	v_and_b32_e32 v3, 28, v215
	v_and_b32_e32 v106, 0x70, v2
	v_add_u32_e32 v15, s0, v98
	v_cmp_lt_u32_e64 s[0:1], 2, v8
	v_mov_b32_e32 v107, v161
	v_cmp_gt_u32_e64 s[74:75], 32, v0
	v_writelane_b32 v254, s0, 33
	v_add3_u32 v172, v10, v1, v3
	v_lshl_add_u32 v173, v0, 2, 0
	v_writelane_b32 v254, s1, 34
	v_lshl_add_u64 v[0:1], s[80:81], 0, v[106:107]
	s_mov_b64 s[0:1], 0xc200000
	v_and_b32_e32 v160, 0xf0, v2
	v_lshl_add_u64 v[108:109], v[0:1], 0, s[0:1]
	v_lshl_add_u64 v[0:1], s[80:81], 0, v[160:161]
	s_mov_b64 s[0:1], 0xc280000
	v_ashrrev_i32_e32 v193, 4, v162
	v_lshl_add_u64 v[110:111], v[0:1], 0, s[0:1]
	s_movk_i32 s0, 0x108
	v_readlane_b32 s4, v253, 9
	v_mul_lo_u32 v0, v193, s0
	v_ashrrev_i32_e32 v104, 3, v162
	v_add_u32_e32 v1, s4, v0
	v_add_u32_e32 v0, 0x200, v162
	v_ashrrev_i32_e32 v195, 4, v0
	v_ashrrev_i32_e32 v194, 3, v0
	v_mul_lo_u32 v0, v195, s0
	v_ashrrev_i32_e32 v105, 31, v104
	s_movk_i32 s0, 0x88
	v_bfe_u32 v112, v162, 3, 5
	v_lshlrev_b32_e32 v112, 5, v112
	v_bfe_u32 v113, v162, 8, 1
	v_lshl_or_b32 v112, v113, 11, v112
	v_bfe_u32 v113, v162, 2, 1
	v_lshl_or_b32 v112, v113, 12, v112
	v_bfe_u32 v113, v162, 1, 1
	v_lshl_or_b32 v112, v113, 10, v112
	v_and_b32_e32 v113, 1, v162
	v_lshl_or_b32 v112, v113, 4, v112
	v_and_b32_e32 v113, 7, v162
	v_lshlrev_b32_e32 v113, 4, v113
	v_sub_u32_e32 v112, v112, v113
	v_mov_b32_e32 v113, 0
	v_mul_lo_u32 v105, v104, s0
	v_lshl_or_b32 v7, v7, 5, v102
	s_add_i32 s0, 0, 0x2000
	v_add_u32_e32 v197, s0, v7
	s_mov_b32 s0, -1
	v_writelane_b32 v254, s0, 35
	v_and_b32_e32 v96, 3, v215
	v_readlane_b32 s0, v254, 7
	s_mov_b32 s5, s0
	v_cmp_gt_i32_e64 s[0:1], 64, v162
	v_cmp_eq_u32_e64 s[12:13], 0, v96
	v_cmp_eq_u32_e64 s[14:15], 0, v8
	v_writelane_b32 v254, s0, 37
	v_cmp_ne_u32_e64 s[90:91], 0, v8
	s_movk_i32 s3, 0x90
	v_writelane_b32 v254, s1, 38
	s_lshl_b64 s[0:1], s[92:93], 2
	v_writelane_b32 v254, s0, 39
	v_cmp_lt_u32_e64 s[94:95], 1, v8
	v_mul_lo_u32 v107, v104, s3
	v_writelane_b32 v254, s1, 40
	v_writelane_b32 v254, s12, 41
	v_mul_lo_u32 v2, v194, s3
	v_add_u32_e32 v16, s4, v0
	v_writelane_b32 v254, s13, 42
	v_writelane_b32 v254, s14, 43
	v_lshlrev_b32_e32 v0, 3, v215
	v_mul_u32_u24_e32 v3, 0x108, v8
	v_writelane_b32 v254, s15, 44
	v_writelane_b32 v254, s90, 45
	v_add_u32_e32 v4, s4, v98
	v_add_u32_e32 v10, 0, v107
	v_writelane_b32 v254, s91, 46
	v_add_u32_e32 v2, 0, v2
	v_and_b32_e32 v0, 56, v0
	v_lshl_or_b32 v7, v168, 7, v9
	v_writelane_b32 v254, s94, 47
	v_and_b32_e32 v100, 32, v215
	s_mov_b32 s84, 0
	v_mul_u32_u24_e32 v175, 0x88, v8
	v_or_b32_e32 v178, 2, v168
	v_or_b32_e32 v179, 4, v168
	v_or_b32_e32 v180, 6, v168
	v_or_b32_e32 v181, 8, v168
	v_or_b32_e32 v182, 10, v168
	v_or_b32_e32 v183, 12, v168
	v_or_b32_e32 v184, 14, v168
	v_or_b32_e32 v185, 16, v168
	v_or_b32_e32 v186, 18, v168
	v_or_b32_e32 v187, 20, v168
	v_or_b32_e32 v188, 22, v168
	v_or_b32_e32 v189, 24, v168
	v_or_b32_e32 v190, 26, v168
	v_or_b32_e32 v191, 28, v168
	v_or_b32_e32 v192, 30, v168
	v_cmp_lt_u32_e64 s[16:17], 3, v8
	v_cmp_lt_u32_e64 s[18:19], 4, v8
	v_cmp_lt_u32_e64 s[20:21], 5, v8
	v_cmp_lt_u32_e64 s[22:23], 6, v8
	v_cmp_lt_u32_e64 s[24:25], 7, v8
	v_cmp_lt_u32_e64 s[26:27], 8, v8
	v_cmp_lt_u32_e64 s[28:29], 9, v8
	v_cmp_lt_u32_e64 s[30:31], 10, v8
	v_cmp_lt_u32_e64 s[34:35], 11, v8
	v_cmp_lt_u32_e64 s[36:37], 12, v8
	v_cmp_lt_u32_e64 s[38:39], 13, v8
	v_cmp_lt_u32_e64 s[40:41], 14, v8
	v_cmp_lt_u32_e64 s[42:43], 15, v8
	v_cmp_lt_u32_e64 s[44:45], 16, v8
	v_cmp_lt_u32_e64 s[46:47], 17, v8
	v_cmp_lt_u32_e64 s[48:49], 18, v8
	v_cmp_lt_u32_e64 s[50:51], 19, v8
	v_cmp_lt_u32_e64 s[52:53], 20, v8
	v_cmp_lt_u32_e64 s[54:55], 21, v8
	v_cmp_lt_u32_e64 s[56:57], 22, v8
	v_cmp_lt_u32_e64 s[58:59], 23, v8
	v_cmp_lt_u32_e64 s[60:61], 24, v8
	v_cmp_lt_u32_e64 s[62:63], 25, v8
	v_cmp_lt_u32_e64 s[64:65], 26, v8
	v_cmp_lt_u32_e64 s[66:67], 27, v8
	v_cmp_lt_u32_e64 s[68:69], 28, v8
	v_ashrrev_i32_e32 v163, 31, v162
	v_add_u32_e32 v198, 0, v7
	v_lshlrev_b32_e32 v199, 2, v8
	v_add_u32_e32 v200, v10, v106
	v_add_u32_e32 v201, v1, v160
	v_add_u32_e32 v202, v2, v106
	v_add_u32_e32 v203, v16, v160
	v_add_u32_e32 v216, v4, v3
	v_add_u32_e32 v217, v5, v3
	v_add_u32_e32 v218, v6, v3
	v_add_u32_e32 v219, v11, v3
	v_add_u32_e32 v220, v12, v3
	v_add_u32_e32 v221, v13, v3
	v_add_u32_e32 v222, v14, v3
	v_add_u32_e32 v223, v15, v3
	v_lshlrev_b32_e32 v114, 1, v0
	v_lshlrev_b32_e32 v116, 1, v102
	v_cmp_lt_u32_e64 s[70:71], 29, v8
	v_cmp_eq_u32_e64 s[72:73], 31, v8
	v_writelane_b32 v254, s95, 48
	s_branch .LBB0_71

.LBB0_119:
	v_lshlrev_b32_e32 v32, 16, v137
	v_mul_f32_e32 v32, 0xbfb8aa3b, v32
	v_exp_f32_e32 v32, v32
	s_waitcnt lgkmcnt(0)
	s_barrier
	v_add_f32_e32 v32, 1.0, v32
	v_rcp_f32_e32 v32, v32
	s_lshl_b32 s0, 2, s89
	s_add_i32 s0, s0, -1
	s_cmp_lt_i32 s89, 31
	v_pk_mul_f32 v[144:145], v[32:33], v[0:1] op_sel_hi:[0,1]
	s_waitcnt vmcnt(1)
	v_lshlrev_b32_e32 v0, 16, v153
	v_mul_f32_e32 v0, 0xbfb8aa3b, v0
	v_exp_f32_e32 v0, v0
	v_pk_mul_f32 v[140:141], v[32:33], v[2:3] op_sel_hi:[0,1]
	s_cselect_b32 s90, s0, -1
	s_cmp_gt_i32 s89, 8
	v_add_f32_e32 v0, 1.0, v0
	v_rcp_f32_e32 v226, v0
	s_waitcnt vmcnt(0)
	v_lshlrev_b32_e32 v0, 16, v152
	v_mul_f32_e32 v0, 0xbfb8aa3b, v0
	v_exp_f32_e32 v0, v0
	s_cselect_b64 s[80:81], -1, 0
	s_add_i32 s6, s89, -8
	ds_read_b32 v2, v173 offset:8192
	v_add_f32_e32 v0, 1.0, v0
	v_rcp_f32_e32 v227, v0
	ds_read_b32 v0, v172 offset:8192
	s_lshl_b32 s7, -1, s6
	s_waitcnt lgkmcnt(1)
	v_and_b32_e32 v2, s90, v2
	ds_bpermute_b32 v3, v159, v2
	s_lshl_b32 s4, s76, 6
	s_waitcnt lgkmcnt(1)
	v_and_b32_e32 v228, s90, v0
	ds_bpermute_b32 v0, v103, v228
	s_lshl_b32 s0, s76, 7
	s_waitcnt lgkmcnt(1)
	v_or_b32_e32 v2, v2, v3
	ds_bpermute_b32 v3, v158, v2
	v_readlane_b32 s1, v254, 24
	s_waitcnt lgkmcnt(1)
	v_or_b32_e32 v0, v228, v0
	ds_bpermute_b32 v1, v101, v0
	s_add_u32 s5, s1, s0
	s_waitcnt lgkmcnt(1)
	v_or_b32_e32 v2, v2, v3
	ds_bpermute_b32 v3, v103, v2
	v_readlane_b32 s0, v254, 25
	s_waitcnt lgkmcnt(1)
	v_or_b32_e32 v0, v0, v1
	ds_bpermute_b32 v1, v99, v0
	v_pk_mul_f32 v[122:123], v[32:33], v[30:31] op_sel_hi:[0,1]
	s_waitcnt lgkmcnt(1)
	v_or_b32_e32 v2, v2, v3
	ds_bpermute_b32 v3, v101, v2
	v_pk_mul_f32 v[126:127], v[32:33], v[28:29] op_sel_hi:[0,1]
	v_pk_mul_f32 v[132:133], v[32:33], v[26:27] op_sel_hi:[0,1]
	v_pk_mul_f32 v[136:137], v[32:33], v[24:25] op_sel_hi:[0,1]
	v_pk_mul_f32 v[142:143], v[32:33], v[22:23] op_sel_hi:[0,1]
	s_waitcnt lgkmcnt(0)
	v_or_b32_e32 v2, v2, v3
	ds_bpermute_b32 v3, v99, v2
	v_pk_mul_f32 v[146:147], v[32:33], v[20:21] op_sel_hi:[0,1]
	v_pk_mul_f32 v[148:149], v[32:33], v[18:19] op_sel_hi:[0,1]
	v_pk_mul_f32 v[150:151], v[32:33], v[16:17] op_sel_hi:[0,1]
	v_pk_mul_f32 v[120:121], v[32:33], v[14:15] op_sel_hi:[0,1]
	s_waitcnt lgkmcnt(0)
	v_or_b32_e32 v2, v2, v3
	ds_bpermute_b32 v3, v97, v2
	v_pk_mul_f32 v[124:125], v[32:33], v[12:13] op_sel_hi:[0,1]
	v_pk_mul_f32 v[128:129], v[32:33], v[10:11] op_sel_hi:[0,1]
	v_pk_mul_f32 v[130:131], v[32:33], v[8:9] op_sel_hi:[0,1]
	v_pk_mul_f32 v[134:135], v[32:33], v[6:7] op_sel_hi:[0,1]
	s_waitcnt lgkmcnt(0)
	v_or_b32_e32 v2, v2, v3
	v_pk_mul_f32 v[138:139], v[32:33], v[4:5] op_sel_hi:[0,1]
	v_or_b32_e32 v229, v0, v1
	v_readfirstlane_b32 s91, v2
	s_addc_u32 s3, s0, 0
	v_add_u32_e32 v230, 0xfffffe01, v117
	v_add_u32_e32 v231, s85, v104
	s_mov_b64 s[82:83], 0
	s_mov_b64 s[76:77], -1
	s_lshl_b32 s0, s85, 7
	s_mov_b32 s1, s93
.LBB0_120:
	s_and_b64 s[8:9], s[80:81], s[82:83]
	s_and_b64 s[8:9], s[8:9], exec
	s_cselect_b32 s8, s7, -1
	s_and_b32 s12, s8, s90
	s_and_b64 s[8:9], s[76:77], exec
	s_movk_i32 s8, 0x400
	s_cselect_b32 s8, s8, 0x600
	s_add_u32 s78, s5, s8
	s_addc_u32 s79, s3, 0
	s_and_b64 s[8:9], s[76:77], exec
	s_cselect_b32 s8, 0, 0x100
	s_or_b32 s8, s8, s4
	s_lshl_b32 s8, s8, 15
	v_readlane_b32 s9, v254, 29
	s_mov_b32 s88, s84
	s_add_u32 s84, s9, s8
	v_readlane_b32 s8, v254, 31
	s_addc_u32 s85, s8, 0
	v_cndmask_b32_e64 v0, v166, v164, s[76:77]
	s_and_b64 s[8:9], s[82:83], exec
	v_mul_f32_e32 v0, v224, v0
	s_cselect_b32 s8, s6, 0xffffff9c
	s_and_b64 s[10:11], s[76:77], exec
	v_min_f32_e32 v232, 0x42700000, v0
	v_mov_b32_e32 v0, s12
	s_cselect_b32 s9, s91, s12
	v_cndmask_b32_e64 v235, v0, v229, s[76:77]
	v_sub_co_u32_e64 v0, s[10:11], s9, 1
	s_nop 0
	v_readfirstlane_b32 s12, v0
	s_and_b32 s13, s12, s9
	s_ff1_i32_b32 s9, s9
	s_and_b64 s[10:11], s[10:11], exec
	v_sub_co_u32_e64 v0, s[14:15], s13, 1
	s_cselect_b32 s10, -1, s9
	v_readfirstlane_b32 s9, v0
	s_and_b32 s12, s9, s13
	s_ff1_i32_b32 s9, s13
	s_and_b64 s[14:15], s[14:15], exec
	s_cselect_b32 s11, -1, s9
	s_lshl_b32 s14, s10, 6
	v_add_u32_e32 v0, s14, v231
	v_ashrrev_i32_e32 v1, 31, v0
	v_lshlrev_b64 v[0:1], 11, v[0:1]
	v_lshl_add_u64 v[0:1], s[78:79], 0, v[0:1]
	v_mov_b32_e32 v115, v161
	v_lshl_add_u64 v[0:1], v[0:1], 0, v[114:115]
	global_load_dwordx4 v[80:83], v[0:1], off
	v_lshl_add_u64 v[0:1], s[84:85], 0, v[112:113]
	s_max_i32 s9, s11, 0
	v_lshl_add_u64 v[0:1], v[0:1], 0, s[0:1]
	s_lshl_b32 s14, s14, 7
	s_ashr_i32 s15, s14, 31
	s_lshl_b32 s92, s9, 13
	v_lshl_add_u64 v[2:3], s[14:15], 0, v[0:1]
	v_lshl_add_u64 v[0:1], v[0:1], 0, s[92:93]
	v_lshl_add_u64 v[2:3], v[2:3], 0, v[114:115]
	v_lshl_add_u64 v[0:1], v[0:1], 0, v[114:115]
	global_load_dwordx4 v[84:87], v[2:3], off
	global_load_dwordx4 v[92:95], v[0:1], off
	v_lshl_add_u32 v2, s9, 6, v231
	v_ashrrev_i32_e32 v3, 31, v2
	v_lshlrev_b64 v[2:3], 11, v[2:3]
	v_lshl_add_u64 v[2:3], s[78:79], 0, v[2:3]
	v_lshl_add_u64 v[2:3], v[2:3], 0, v[114:115]
	global_load_dwordx4 v[88:91], v[2:3], off
	s_add_u32 s14, s84, s0
	s_mul_i32 s9, s88, 0x4600
	s_addc_u32 s15, s85, 0
	s_add_i32 s13, s9, 0
	s_xor_b32 s9, s88, 1
	s_mul_i32 s84, s9, 0x4600
	s_add_i32 s84, s84, 0
	v_lshl_add_u64 v[0:1], s[14:15], 0, v[112:113]
	v_add_u32_e32 v2, s13, v174
	v_add_u32_e32 v3, s13, v98
	v_add_u32_e32 v4, s84, v174
	v_add_u32_e32 v5, s84, v98
	v_add_u32_e32 v6, s13, v107
	v_add_u32_e32 v7, s13, v105
	v_lshl_add_u64 v[152:153], s[78:79], 0, v[114:115]
	v_lshl_add_u64 v[154:155], v[0:1], 0, v[114:115]
	v_add_u32_e32 v0, s84, v107
	v_add_u32_e32 v1, s84, v105
	v_mov_b32_e32 v115, 0
	s_movk_i32 s13, 0x6400
	v_cndmask_b32_e64 v233, -2.0, v230, s[82:83]
	v_cndmask_b32_e64 v234, -1, v228, s[76:77]
	v_add_u32_e32 v236, v6, v106
	v_add3_u32 v237, v7, v106, s13
	v_add_u32_e32 v238, v2, v170
	v_add_u32_e32 v239, v3, v175
	v_add_u32_e32 v240, v0, v106
	v_add3_u32 v241, v1, v106, s13
	v_add_u32_e32 v242, v4, v170
	v_add_u32_e32 v243, v5, v175
	v_mov_b32_e32 v0, 0
	v_mov_b32_e32 v1, v115
	v_mov_b32_e32 v2, v115
	v_mov_b32_e32 v3, v115
	v_mov_b32_e32 v4, v115
	v_mov_b32_e32 v5, v115
	v_mov_b32_e32 v6, v115
	v_mov_b32_e32 v7, v115
	v_mov_b32_e32 v8, v115
	v_mov_b32_e32 v9, v115
	v_mov_b32_e32 v10, v115
	v_mov_b32_e32 v11, v115
	v_mov_b32_e32 v12, v115
	v_mov_b32_e32 v13, v115
	v_mov_b32_e32 v14, v115
	v_mov_b32_e32 v15, v115
	v_mov_b32_e32 v16, v115
	v_mov_b32_e32 v17, v115
	v_mov_b32_e32 v18, v115
	v_mov_b32_e32 v19, v115
	v_mov_b32_e32 v20, v115
	v_mov_b32_e32 v21, v115
	v_mov_b32_e32 v22, v115
	v_mov_b32_e32 v23, v115
	v_mov_b32_e32 v24, v115
	v_mov_b32_e32 v25, v115
	v_mov_b32_e32 v26, v115
	v_mov_b32_e32 v27, v115
	v_mov_b32_e32 v28, v115
	v_mov_b32_e32 v29, v115
	v_mov_b32_e32 v30, v115
	v_mov_b32_e32 v31, v115
	s_branch .LBB0_123

.LBB0_123:
	s_ff1_i32_b32 s14, s12
	v_sub_co_u32_e64 v32, s[94:95], s12, 1
	s_lshl_b32 s15, s14, 6
	s_and_b64 s[78:79], s[94:95], exec
	s_cselect_b32 s15, 0, s15
	v_readfirstlane_b32 s13, v32
	v_add_u32_e32 v32, s15, v231
	v_ashrrev_i32_e32 v33, 31, v32
	s_waitcnt vmcnt(3)
	ds_write_b128 v236, v[80:83] offset:16384
	s_waitcnt vmcnt(2)
	ds_write2_b64 v237, v[84:85], v[86:87] offset1:1
	v_lshlrev_b64 v[32:33], 11, v[32:33]
	s_waitcnt lgkmcnt(0)
	s_barrier
	v_lshl_add_u64 v[32:33], v[152:153], 0, v[32:33]
	s_lshl_b32 s92, s15, 7
	global_load_dwordx4 v[80:83], v[32:33], off
	v_lshl_add_u64 v[32:33], v[154:155], 0, s[92:93]
	global_load_dwordx4 v[84:87], v[32:33], off
	s_lshl_b32 s15, 1, s10
	v_and_b32_e32 v32, s15, v235
	v_cmp_ne_u32_e32 vcc, 0, v32
	s_and_saveexec_b64 s[84:85], vcc
	s_cbranch_execz .LBB0_127
	ds_read_b128 v[244:247], v238 offset:16384
	v_and_b32_e32 v32, s15, v234
	v_cmp_ne_u32_e32 vcc, 0, v32
	s_cmp_lg_u32 s10, s89
	s_cselect_b64 s[78:79], -1, 0
	v_cndmask_b32_e64 v32, v208, -v232, vcc
	v_mov_b32_e32 v33, v32
	v_mov_b32_e32 v34, v32
	v_mov_b32_e32 v35, v32
	v_mov_b32_e32 v36, v32
	v_mov_b32_e32 v37, v32
	v_mov_b32_e32 v38, v32
	v_mov_b32_e32 v39, v32
	v_mov_b32_e32 v40, v32
	v_mov_b32_e32 v41, v32
	v_mov_b32_e32 v42, v32
	v_mov_b32_e32 v43, v32
	v_mov_b32_e32 v44, v32
	v_mov_b32_e32 v45, v32
	v_mov_b32_e32 v46, v32
	v_mov_b32_e32 v47, v32
	s_cmp_lg_u32 s10, s8
	s_cselect_b64 vcc, -1, 0
	s_waitcnt lgkmcnt(0)
	v_mfma_f32_32x32x16_bf16 v[48:63], v[244:247], v[64:67], v[32:47]
	ds_read_b128 v[244:247], v238 offset:20992
	s_and_b64 s[78:79], s[78:79], vcc
	s_and_b64 vcc, exec, s[78:79]
	s_waitcnt lgkmcnt(0)
	v_mfma_f32_32x32x16_bf16 v[32:47], v[244:247], v[64:67], v[32:47]
	ds_read_b128 v[244:247], v238 offset:16416
	s_waitcnt lgkmcnt(0)
	v_mfma_f32_32x32x16_bf16 v[48:63], v[244:247], v[68:71], v[48:63]
	ds_read_b128 v[244:247], v238 offset:21024
	s_waitcnt lgkmcnt(0)
	v_mfma_f32_32x32x16_bf16 v[32:47], v[244:247], v[68:71], v[32:47]
	ds_read_b128 v[244:247], v238 offset:16448
	s_waitcnt lgkmcnt(0)
	v_mfma_f32_32x32x16_bf16 v[48:63], v[244:247], v[72:75], v[48:63]
	ds_read_b128 v[244:247], v238 offset:21056
	s_waitcnt lgkmcnt(0)
	v_mfma_f32_32x32x16_bf16 v[32:47], v[244:247], v[72:75], v[32:47]
	ds_read_b128 v[244:247], v238 offset:16480
	s_waitcnt lgkmcnt(0)
	v_mfma_f32_32x32x16_bf16 v[48:63], v[244:247], v[76:79], v[48:63]
	ds_read_b128 v[244:247], v238 offset:21088
	s_waitcnt lgkmcnt(0)
	v_mfma_f32_32x32x16_bf16 v[32:47], v[244:247], v[76:79], v[32:47]
	s_cbranch_vccnz .LBB0_126
	v_lshl_or_b32 v156, s10, 6, v102
	v_cmp_lt_i32_e32 vcc, v156, v233
	v_cmp_gt_i32_e64 s[78:79], v156, v117
	s_or_b64 vcc, vcc, s[78:79]
	v_or_b32_e32 v157, 32, v156
	s_nop 2
	v_cndmask_b32_e32 v48, v48, v208, vcc
	v_cmp_lt_i32_e32 vcc, v157, v233
	v_cmp_gt_i32_e64 s[78:79], v157, v117
	s_or_b64 vcc, vcc, s[78:79]
	v_or_b32_e32 v157, 1, v156
	v_cndmask_b32_e32 v32, v32, v208, vcc
	v_cmp_lt_i32_e32 vcc, v157, v233
	v_cmp_ge_i32_e64 s[78:79], v156, v117
	s_or_b64 vcc, s[78:79], vcc
	v_or_b32_e32 v157, 33, v156
	v_cndmask_b32_e32 v49, v49, v208, vcc
	v_cmp_lt_i32_e32 vcc, v157, v233
	v_cmp_gt_i32_e64 s[78:79], v157, v117
	s_or_b64 vcc, vcc, s[78:79]
	v_or_b32_e32 v157, 2, v156
	v_cndmask_b32_e32 v33, v33, v208, vcc
	v_cmp_lt_i32_e32 vcc, v157, v233
	v_cmp_gt_i32_e64 s[78:79], v157, v117
	s_or_b64 vcc, vcc, s[78:79]
	v_or_b32_e32 v157, 34, v156
	v_cndmask_b32_e32 v50, v50, v208, vcc
	v_cmp_lt_i32_e32 vcc, v157, v233
	v_cmp_gt_i32_e64 s[78:79], v157, v117
	s_or_b64 vcc, vcc, s[78:79]
	v_or_b32_e32 v157, 3, v156
	v_cndmask_b32_e32 v34, v34, v208, vcc
	v_cmp_lt_i32_e32 vcc, v157, v233
	v_cmp_gt_i32_e64 s[78:79], v157, v117
	s_or_b64 vcc, vcc, s[78:79]
	v_or_b32_e32 v157, 35, v156
	v_cndmask_b32_e32 v51, v51, v208, vcc
	v_cmp_lt_i32_e32 vcc, v157, v233
	v_cmp_gt_i32_e64 s[78:79], v157, v117
	s_or_b64 vcc, vcc, s[78:79]
	v_or_b32_e32 v157, 8, v156
	v_cndmask_b32_e32 v35, v35, v208, vcc
	v_cmp_lt_i32_e32 vcc, v157, v233
	v_cmp_gt_i32_e64 s[78:79], v157, v117
	s_or_b64 vcc, vcc, s[78:79]
	v_or_b32_e32 v157, 40, v156
	v_cndmask_b32_e32 v52, v52, v208, vcc
	v_cmp_lt_i32_e32 vcc, v157, v233
	v_cmp_gt_i32_e64 s[78:79], v157, v117
	s_or_b64 vcc, vcc, s[78:79]
	v_or_b32_e32 v157, 9, v156
	v_cndmask_b32_e32 v36, v36, v208, vcc
	v_cmp_lt_i32_e32 vcc, v157, v233
	v_cmp_gt_i32_e64 s[78:79], v157, v117
	s_or_b64 vcc, vcc, s[78:79]
	v_or_b32_e32 v157, 41, v156
	v_cndmask_b32_e32 v53, v53, v208, vcc
	v_cmp_lt_i32_e32 vcc, v157, v233
	v_cmp_gt_i32_e64 s[78:79], v157, v117
	s_or_b64 vcc, vcc, s[78:79]
	v_or_b32_e32 v157, 10, v156
	v_cndmask_b32_e32 v37, v37, v208, vcc
	v_cmp_lt_i32_e32 vcc, v157, v233
	v_cmp_gt_i32_e64 s[78:79], v157, v117
	s_or_b64 vcc, vcc, s[78:79]
	v_or_b32_e32 v157, 42, v156
	v_cndmask_b32_e32 v54, v54, v208, vcc
	v_cmp_lt_i32_e32 vcc, v157, v233
	v_cmp_gt_i32_e64 s[78:79], v157, v117
	s_or_b64 vcc, vcc, s[78:79]
	v_or_b32_e32 v157, 11, v156
	v_cndmask_b32_e32 v38, v38, v208, vcc
	v_cmp_lt_i32_e32 vcc, v157, v233
	v_cmp_gt_i32_e64 s[78:79], v157, v117
	s_or_b64 vcc, vcc, s[78:79]
	v_or_b32_e32 v157, 43, v156
	v_cndmask_b32_e32 v55, v55, v208, vcc
	v_cmp_lt_i32_e32 vcc, v157, v233
	v_cmp_gt_i32_e64 s[78:79], v157, v117
	s_or_b64 vcc, vcc, s[78:79]
	v_or_b32_e32 v157, 16, v156
	v_cndmask_b32_e32 v39, v39, v208, vcc
	v_cmp_lt_i32_e32 vcc, v157, v233
	v_cmp_gt_i32_e64 s[78:79], v157, v117
	s_or_b64 vcc, vcc, s[78:79]
	v_or_b32_e32 v157, 48, v156
	v_cndmask_b32_e32 v56, v56, v208, vcc
	v_cmp_lt_i32_e32 vcc, v157, v233
	v_cmp_gt_i32_e64 s[78:79], v157, v117
	s_or_b64 vcc, vcc, s[78:79]
	v_or_b32_e32 v157, 17, v156
	v_cndmask_b32_e32 v40, v40, v208, vcc
	v_cmp_lt_i32_e32 vcc, v157, v233
	v_cmp_gt_i32_e64 s[78:79], v157, v117
	s_or_b64 vcc, vcc, s[78:79]
	v_or_b32_e32 v157, 49, v156
	v_cndmask_b32_e32 v57, v57, v208, vcc
	v_cmp_lt_i32_e32 vcc, v157, v233
	v_cmp_gt_i32_e64 s[78:79], v157, v117
	s_or_b64 vcc, vcc, s[78:79]
	v_or_b32_e32 v157, 18, v156
	v_cndmask_b32_e32 v41, v41, v208, vcc
	v_cmp_lt_i32_e32 vcc, v157, v233
	v_cmp_gt_i32_e64 s[78:79], v157, v117
	s_or_b64 vcc, vcc, s[78:79]
	v_or_b32_e32 v157, 50, v156
	v_cndmask_b32_e32 v58, v58, v208, vcc
	v_cmp_lt_i32_e32 vcc, v157, v233
	v_cmp_gt_i32_e64 s[78:79], v157, v117
	s_or_b64 vcc, vcc, s[78:79]
	v_or_b32_e32 v157, 19, v156
	v_cndmask_b32_e32 v42, v42, v208, vcc
	v_cmp_lt_i32_e32 vcc, v157, v233
	v_cmp_gt_i32_e64 s[78:79], v157, v117
	s_or_b64 vcc, vcc, s[78:79]
	v_or_b32_e32 v157, 51, v156
	v_cndmask_b32_e32 v59, v59, v208, vcc
	v_cmp_lt_i32_e32 vcc, v157, v233
	v_cmp_gt_i32_e64 s[78:79], v157, v117
	s_or_b64 vcc, vcc, s[78:79]
	v_or_b32_e32 v157, 24, v156
	v_cndmask_b32_e32 v43, v43, v208, vcc
	v_cmp_lt_i32_e32 vcc, v157, v233
	v_cmp_gt_i32_e64 s[78:79], v157, v117
	s_or_b64 vcc, vcc, s[78:79]
	v_or_b32_e32 v157, 56, v156
	v_cndmask_b32_e32 v60, v60, v208, vcc
	v_cmp_lt_i32_e32 vcc, v157, v233
	v_cmp_gt_i32_e64 s[78:79], v157, v117
	s_or_b64 vcc, vcc, s[78:79]
	v_or_b32_e32 v157, 25, v156
	v_cndmask_b32_e32 v44, v44, v208, vcc
	v_cmp_lt_i32_e32 vcc, v157, v233
	v_cmp_gt_i32_e64 s[78:79], v157, v117
	s_or_b64 vcc, vcc, s[78:79]
	v_or_b32_e32 v157, 57, v156
	v_cndmask_b32_e32 v61, v61, v208, vcc
	v_cmp_lt_i32_e32 vcc, v157, v233
	v_cmp_gt_i32_e64 s[78:79], v157, v117
	s_or_b64 vcc, vcc, s[78:79]
	v_or_b32_e32 v157, 26, v156
	v_cndmask_b32_e32 v45, v45, v208, vcc
	v_cmp_lt_i32_e32 vcc, v157, v233
	v_cmp_gt_i32_e64 s[78:79], v157, v117
	s_or_b64 vcc, vcc, s[78:79]
	v_or_b32_e32 v157, 58, v156
	v_cndmask_b32_e32 v62, v62, v208, vcc
	v_cmp_lt_i32_e32 vcc, v157, v233
	v_cmp_gt_i32_e64 s[78:79], v157, v117
	s_or_b64 vcc, vcc, s[78:79]
	v_or_b32_e32 v157, 27, v156
	v_cndmask_b32_e32 v46, v46, v208, vcc
	v_cmp_lt_i32_e32 vcc, v157, v233
	v_cmp_gt_i32_e64 s[78:79], v157, v117
	s_or_b64 vcc, vcc, s[78:79]
	v_or_b32_e32 v156, 59, v156
	v_cndmask_b32_e32 v63, v63, v208, vcc
	v_cmp_lt_i32_e32 vcc, v156, v233
	v_cmp_gt_i32_e64 s[78:79], v156, v117
	s_or_b64 vcc, vcc, s[78:79]
	v_cndmask_b32_e32 v47, v47, v208, vcc

.LBB0_127:
	s_or_b64 exec, exec, s[84:85]
	s_cmp_lt_i32 s11, 0
	s_cbranch_scc1 .LBB0_131
	s_and_b32 s12, s13, s12
	v_sub_co_u32_e64 v36, s[78:79], s12, 1
	s_ff1_i32_b32 s10, s12
	s_and_b64 s[78:79], s[78:79], exec
	s_cselect_b32 s13, -1, s10
	s_max_i32 s10, s13, 0
	v_lshl_add_u32 v32, s10, 6, v231
	v_ashrrev_i32_e32 v33, 31, v32
	s_waitcnt vmcnt(2)
	ds_write_b128 v240, v[88:91] offset:16384
	ds_write2_b64 v241, v[92:93], v[94:95] offset1:1
	v_lshlrev_b64 v[32:33], 11, v[32:33]
	s_waitcnt lgkmcnt(0)
	s_barrier
	v_lshl_add_u64 v[32:33], v[152:153], 0, v[32:33]
	s_lshl_b32 s92, s10, 13
	v_lshl_add_u64 v[34:35], v[154:155], 0, s[92:93]
	global_load_dwordx4 v[88:91], v[32:33], off
	global_load_dwordx4 v[92:95], v[34:35], off
	s_lshl_b32 s10, 1, s11
	v_and_b32_e32 v32, s10, v235
	v_readfirstlane_b32 s92, v36
	v_cmp_ne_u32_e32 vcc, 0, v32
	s_and_saveexec_b64 s[84:85], vcc
	s_cbranch_execz .LBB0_122
	ds_read_b128 v[244:247], v242 offset:16384
	v_and_b32_e32 v32, s10, v234
	v_cmp_ne_u32_e32 vcc, 0, v32
	s_cmp_lg_u32 s11, s89
	s_cselect_b64 s[78:79], -1, 0
	v_cndmask_b32_e64 v32, v208, -v232, vcc
	v_mov_b32_e32 v33, v32
	v_mov_b32_e32 v34, v32
	v_mov_b32_e32 v35, v32
	v_mov_b32_e32 v36, v32
	v_mov_b32_e32 v37, v32
	v_mov_b32_e32 v38, v32
	v_mov_b32_e32 v39, v32
	v_mov_b32_e32 v40, v32
	v_mov_b32_e32 v41, v32
	v_mov_b32_e32 v42, v32
	v_mov_b32_e32 v43, v32
	v_mov_b32_e32 v44, v32
	v_mov_b32_e32 v45, v32
	v_mov_b32_e32 v46, v32
	v_mov_b32_e32 v47, v32
	s_cmp_lg_u32 s11, s8
	s_cselect_b64 vcc, -1, 0
	s_waitcnt lgkmcnt(0)
	v_mfma_f32_32x32x16_bf16 v[48:63], v[244:247], v[64:67], v[32:47]
	ds_read_b128 v[244:247], v242 offset:20992
	s_and_b64 s[78:79], s[78:79], vcc
	s_and_b64 vcc, exec, s[78:79]
	s_waitcnt lgkmcnt(0)
	v_mfma_f32_32x32x16_bf16 v[32:47], v[244:247], v[64:67], v[32:47]
	ds_read_b128 v[244:247], v242 offset:16416
	s_waitcnt lgkmcnt(0)
	v_mfma_f32_32x32x16_bf16 v[48:63], v[244:247], v[68:71], v[48:63]
	ds_read_b128 v[244:247], v242 offset:21024
	s_waitcnt lgkmcnt(0)
	v_mfma_f32_32x32x16_bf16 v[32:47], v[244:247], v[68:71], v[32:47]
	ds_read_b128 v[244:247], v242 offset:16448
	s_waitcnt lgkmcnt(0)
	v_mfma_f32_32x32x16_bf16 v[48:63], v[244:247], v[72:75], v[48:63]
	ds_read_b128 v[244:247], v242 offset:21056
	s_waitcnt lgkmcnt(0)
	v_mfma_f32_32x32x16_bf16 v[32:47], v[244:247], v[72:75], v[32:47]
	ds_read_b128 v[244:247], v242 offset:16480
	s_waitcnt lgkmcnt(0)
	v_mfma_f32_32x32x16_bf16 v[48:63], v[244:247], v[76:79], v[48:63]
	ds_read_b128 v[244:247], v242 offset:21088
	s_waitcnt lgkmcnt(0)
	v_mfma_f32_32x32x16_bf16 v[32:47], v[244:247], v[76:79], v[32:47]
	s_cbranch_vccnz .LBB0_121
	v_lshl_or_b32 v156, s11, 6, v102
	v_cmp_lt_i32_e32 vcc, v156, v233
	v_cmp_gt_i32_e64 s[78:79], v156, v117
	s_or_b64 vcc, vcc, s[78:79]
	v_or_b32_e32 v157, 32, v156
	s_nop 2
	v_cndmask_b32_e32 v48, v48, v208, vcc
	v_cmp_lt_i32_e32 vcc, v157, v233
	v_cmp_gt_i32_e64 s[78:79], v157, v117
	s_or_b64 vcc, vcc, s[78:79]
	v_or_b32_e32 v157, 1, v156
	v_cndmask_b32_e32 v32, v32, v208, vcc
	v_cmp_lt_i32_e32 vcc, v157, v233
	v_cmp_ge_i32_e64 s[78:79], v156, v117
	s_or_b64 vcc, s[78:79], vcc
	v_or_b32_e32 v157, 33, v156
	v_cndmask_b32_e32 v49, v49, v208, vcc
	v_cmp_lt_i32_e32 vcc, v157, v233
	v_cmp_gt_i32_e64 s[78:79], v157, v117
	s_or_b64 vcc, vcc, s[78:79]
	v_or_b32_e32 v157, 2, v156
	v_cndmask_b32_e32 v33, v33, v208, vcc
	v_cmp_lt_i32_e32 vcc, v157, v233
	v_cmp_gt_i32_e64 s[78:79], v157, v117
	s_or_b64 vcc, vcc, s[78:79]
	v_or_b32_e32 v157, 34, v156
	v_cndmask_b32_e32 v50, v50, v208, vcc
	v_cmp_lt_i32_e32 vcc, v157, v233
	v_cmp_gt_i32_e64 s[78:79], v157, v117
	s_or_b64 vcc, vcc, s[78:79]
	v_or_b32_e32 v157, 3, v156
	v_cndmask_b32_e32 v34, v34, v208, vcc
	v_cmp_lt_i32_e32 vcc, v157, v233
	v_cmp_gt_i32_e64 s[78:79], v157, v117
	s_or_b64 vcc, vcc, s[78:79]
	v_or_b32_e32 v157, 35, v156
	v_cndmask_b32_e32 v51, v51, v208, vcc
	v_cmp_lt_i32_e32 vcc, v157, v233
	v_cmp_gt_i32_e64 s[78:79], v157, v117
	s_or_b64 vcc, vcc, s[78:79]
	v_or_b32_e32 v157, 8, v156
	v_cndmask_b32_e32 v35, v35, v208, vcc
	v_cmp_lt_i32_e32 vcc, v157, v233
	v_cmp_gt_i32_e64 s[78:79], v157, v117
	s_or_b64 vcc, vcc, s[78:79]
	v_or_b32_e32 v157, 40, v156
	v_cndmask_b32_e32 v52, v52, v208, vcc
	v_cmp_lt_i32_e32 vcc, v157, v233
	v_cmp_gt_i32_e64 s[78:79], v157, v117
	s_or_b64 vcc, vcc, s[78:79]
	v_or_b32_e32 v157, 9, v156
	v_cndmask_b32_e32 v36, v36, v208, vcc
	v_cmp_lt_i32_e32 vcc, v157, v233
	v_cmp_gt_i32_e64 s[78:79], v157, v117
	s_or_b64 vcc, vcc, s[78:79]
	v_or_b32_e32 v157, 41, v156
	v_cndmask_b32_e32 v53, v53, v208, vcc
	v_cmp_lt_i32_e32 vcc, v157, v233
	v_cmp_gt_i32_e64 s[78:79], v157, v117
	s_or_b64 vcc, vcc, s[78:79]
	v_or_b32_e32 v157, 10, v156
	v_cndmask_b32_e32 v37, v37, v208, vcc
	v_cmp_lt_i32_e32 vcc, v157, v233
	v_cmp_gt_i32_e64 s[78:79], v157, v117
	s_or_b64 vcc, vcc, s[78:79]
	v_or_b32_e32 v157, 42, v156
	v_cndmask_b32_e32 v54, v54, v208, vcc
	v_cmp_lt_i32_e32 vcc, v157, v233
	v_cmp_gt_i32_e64 s[78:79], v157, v117
	s_or_b64 vcc, vcc, s[78:79]
	v_or_b32_e32 v157, 11, v156
	v_cndmask_b32_e32 v38, v38, v208, vcc
	v_cmp_lt_i32_e32 vcc, v157, v233
	v_cmp_gt_i32_e64 s[78:79], v157, v117
	s_or_b64 vcc, vcc, s[78:79]
	v_or_b32_e32 v157, 43, v156
	v_cndmask_b32_e32 v55, v55, v208, vcc
	v_cmp_lt_i32_e32 vcc, v157, v233
	v_cmp_gt_i32_e64 s[78:79], v157, v117
	s_or_b64 vcc, vcc, s[78:79]
	v_or_b32_e32 v157, 16, v156
	v_cndmask_b32_e32 v39, v39, v208, vcc
	v_cmp_lt_i32_e32 vcc, v157, v233
	v_cmp_gt_i32_e64 s[78:79], v157, v117
	s_or_b64 vcc, vcc, s[78:79]
	v_or_b32_e32 v157, 48, v156
	v_cndmask_b32_e32 v56, v56, v208, vcc
	v_cmp_lt_i32_e32 vcc, v157, v233
	v_cmp_gt_i32_e64 s[78:79], v157, v117
	s_or_b64 vcc, vcc, s[78:79]
	v_or_b32_e32 v157, 17, v156
	v_cndmask_b32_e32 v40, v40, v208, vcc
	v_cmp_lt_i32_e32 vcc, v157, v233
	v_cmp_gt_i32_e64 s[78:79], v157, v117
	s_or_b64 vcc, vcc, s[78:79]
	v_or_b32_e32 v157, 49, v156
	v_cndmask_b32_e32 v57, v57, v208, vcc
	v_cmp_lt_i32_e32 vcc, v157, v233
	v_cmp_gt_i32_e64 s[78:79], v157, v117
	s_or_b64 vcc, vcc, s[78:79]
	v_or_b32_e32 v157, 18, v156
	v_cndmask_b32_e32 v41, v41, v208, vcc
	v_cmp_lt_i32_e32 vcc, v157, v233
	v_cmp_gt_i32_e64 s[78:79], v157, v117
	s_or_b64 vcc, vcc, s[78:79]
	v_or_b32_e32 v157, 50, v156
	v_cndmask_b32_e32 v58, v58, v208, vcc
	v_cmp_lt_i32_e32 vcc, v157, v233
	v_cmp_gt_i32_e64 s[78:79], v157, v117
	s_or_b64 vcc, vcc, s[78:79]
	v_or_b32_e32 v157, 19, v156
	v_cndmask_b32_e32 v42, v42, v208, vcc
	v_cmp_lt_i32_e32 vcc, v157, v233
	v_cmp_gt_i32_e64 s[78:79], v157, v117
	s_or_b64 vcc, vcc, s[78:79]
	v_or_b32_e32 v157, 51, v156
	v_cndmask_b32_e32 v59, v59, v208, vcc
	v_cmp_lt_i32_e32 vcc, v157, v233
	v_cmp_gt_i32_e64 s[78:79], v157, v117
	s_or_b64 vcc, vcc, s[78:79]
	v_or_b32_e32 v157, 24, v156
	v_cndmask_b32_e32 v43, v43, v208, vcc
	v_cmp_lt_i32_e32 vcc, v157, v233
	v_cmp_gt_i32_e64 s[78:79], v157, v117
	s_or_b64 vcc, vcc, s[78:79]
	v_or_b32_e32 v157, 56, v156
	v_cndmask_b32_e32 v60, v60, v208, vcc
	v_cmp_lt_i32_e32 vcc, v157, v233
	v_cmp_gt_i32_e64 s[78:79], v157, v117
	s_or_b64 vcc, vcc, s[78:79]
	v_or_b32_e32 v157, 25, v156
	v_cndmask_b32_e32 v44, v44, v208, vcc
	v_cmp_lt_i32_e32 vcc, v157, v233
	v_cmp_gt_i32_e64 s[78:79], v157, v117
	s_or_b64 vcc, vcc, s[78:79]
	v_or_b32_e32 v157, 57, v156
	v_cndmask_b32_e32 v61, v61, v208, vcc
	v_cmp_lt_i32_e32 vcc, v157, v233
	v_cmp_gt_i32_e64 s[78:79], v157, v117
	s_or_b64 vcc, vcc, s[78:79]
	v_or_b32_e32 v157, 26, v156
	v_cndmask_b32_e32 v45, v45, v208, vcc
	v_cmp_lt_i32_e32 vcc, v157, v233
	v_cmp_gt_i32_e64 s[78:79], v157, v117
	s_or_b64 vcc, vcc, s[78:79]
	v_or_b32_e32 v157, 58, v156
	v_cndmask_b32_e32 v62, v62, v208, vcc
	v_cmp_lt_i32_e32 vcc, v157, v233
	v_cmp_gt_i32_e64 s[78:79], v157, v117
	s_or_b64 vcc, vcc, s[78:79]
	v_or_b32_e32 v157, 27, v156
	v_cndmask_b32_e32 v46, v46, v208, vcc
	v_cmp_lt_i32_e32 vcc, v157, v233
	v_cmp_gt_i32_e64 s[78:79], v157, v117
	s_or_b64 vcc, vcc, s[78:79]
	v_or_b32_e32 v156, 59, v156
	v_cndmask_b32_e32 v63, v63, v208, vcc
	v_cmp_lt_i32_e32 vcc, v156, v233
	v_cmp_gt_i32_e64 s[78:79], v156, v117
	s_or_b64 vcc, vcc, s[78:79]
	v_cndmask_b32_e32 v47, v47, v208, vcc
	s_branch .LBB0_121

.LBB0_135:
	s_andn2_b64 vcc, exec, s[0:1]
	s_cbranch_vccnz .LBB0_146
	s_cmpk_gt_i32 s79, 0x3ff
	s_cbranch_scc1 .LBB0_146
	v_bfe_u32 v1, v215, 5, 1
	v_ashrrev_i32_e32 v0, 1, v162
	v_lshlrev_b32_e32 v160, 3, v1
	v_and_b32_e32 v111, 0xffffffe0, v0
	v_lshlrev_b32_e32 v0, 2, v1
	s_waitcnt lgkmcnt(0)
	v_lshl_add_u64 v[2:3], s[80:81], 0, v[160:161]
	s_mov_b64 s[4:5], 0x10400000
	v_and_b32_e32 v110, 31, v215
	s_waitcnt vmcnt(0)
	v_lshl_add_u64 v[80:81], v[2:3], 0, s[4:5]
	v_or_b32_e32 v2, 1, v0
	v_cmp_lt_u32_e64 s[6:7], v2, v110
	v_or_b32_e32 v2, 2, v0
	v_cmp_lt_u32_e64 s[8:9], v2, v110
	v_or_b32_e32 v2, 3, v0
	v_cmp_lt_u32_e64 s[10:11], v2, v110
	v_or_b32_e32 v2, 9, v0
	v_cmp_lt_u32_e64 s[12:13], v2, v110
	v_or_b32_e32 v2, 10, v0
	v_cmp_lt_u32_e64 s[16:17], v2, v110
	v_or_b32_e32 v2, 11, v0
	v_cmp_lt_u32_e64 s[18:19], v2, v110
	v_or_b32_e32 v2, 17, v0
	v_cmp_lt_u32_e64 s[20:21], v2, v110
	v_or_b32_e32 v2, 18, v0
	s_mov_b64 s[60:61], s[24:25]
	v_cmp_lt_u32_e64 s[24:25], v2, v110
	v_or_b32_e32 v2, 19, v0
	s_mov_b64 s[52:53], s[26:27]
	v_or_b32_e32 v3, 8, v0
	v_cmp_lt_u32_e64 s[26:27], v2, v110
	v_or_b32_e32 v2, 25, v0
	s_mov_b32 s58, s29
	v_cmp_lt_u32_e64 s[14:15], v3, v110
	v_or_b32_e32 v3, 16, v0
	v_cmp_lt_u32_e64 s[28:29], v2, v110
	v_or_b32_e32 v2, 26, v0
	s_mov_b64 s[62:63], s[22:23]
	v_cmp_lt_u32_e64 s[22:23], v3, v110
	v_or_b32_e32 v3, 24, v0
	v_cmp_lt_u32_e64 s[34:35], v2, v110
	v_or_b32_e32 v2, 27, v0
	v_readlane_b32 s38, v254, 10
	s_add_u32 s0, s80, 0x12400000
	v_lshlrev_b32_e32 v4, 14, v110
	v_cmp_lt_u32_e64 s[30:31], v3, v110
	v_cmp_lt_u32_e64 s[36:37], v2, v110
	v_lshlrev_b32_e32 v2, 4, v1
	v_mov_b32_e32 v3, v161
	v_readlane_b32 s39, v254, 11
	s_addc_u32 s1, s81, 0
	v_cmp_eq_u32_e32 vcc, 0, v1
	v_cmp_lt_u32_e64 s[4:5], v0, v110
	v_lshl_add_u64 v[82:83], s[38:39], 0, v[2:3]
	s_lshl_b32 s3, s79, 5
	s_lshl_b32 s46, s33, 5
	s_lshl_b32 s47, s79, 2
	s_lshl_b32 s48, s33, 2
	s_waitcnt vmcnt(8)
	v_lshlrev_b32_e32 v84, 1, v160
	v_lshlrev_b32_e32 v112, 5, v110
	v_lshlrev_b32_e32 v86, 1, v0
	s_mov_b32 s49, s79
	s_branch .LBB0_140

.LBB0_140:
	s_ashr_i32 s44, s49, 3
	s_lshl_b32 s39, s49, 2
	s_and_b32 s38, s44, 0x1ffffe0
	s_and_b32 s40, s39, 16
	s_or_b32 s38, s38, s40
	s_lshl_b32 s42, s38, 7
	s_lshl_b32 s38, s49, 5
	s_and_b32 s38, s38, 0x700
	v_add_u32_e32 v160, s38, v111
	s_bfe_u32 s40, s49, 0x20006
	s_and_b32 s39, s39, 12
	v_add_u32_e32 v0, s42, v160
	s_or_b32 s45, s39, s40
	v_or_b32_e32 v88, v0, v110
	v_ashrrev_i32_e32 v87, 5, v160
	v_mov_b32_e32 v15, 0
	v_ashrrev_i32_e32 v89, 31, v88
	s_lshl_b32 s50, s45, 6
	v_cmp_lt_i32_e64 s[38:39], -1, v87
	v_mov_b32_e32 v14, v15
	v_mov_b32_e32 v13, v15
	v_mov_b32_e32 v12, v15
	v_mov_b32_e32 v11, v15
	v_mov_b32_e32 v10, v15
	v_mov_b32_e32 v9, v15
	v_mov_b32_e32 v8, v15
	v_mov_b32_e32 v7, v15
	s_waitcnt lgkmcnt(1)
	v_mov_b32_e32 v6, v15
	s_waitcnt lgkmcnt(0)
	v_mov_b32_e32 v5, v15
	v_mov_b32_e32 v4, v15
	v_mov_b32_e32 v3, v15
	v_mov_b32_e32 v2, v15
	v_mov_b32_e32 v1, v15
	v_mov_b32_e32 v0, v15
	v_mov_b32_e32 v31, v15
	v_mov_b32_e32 v30, v15
	v_mov_b32_e32 v29, v15
	v_mov_b32_e32 v28, v15
	v_mov_b32_e32 v27, v15
	v_mov_b32_e32 v26, v15
	v_mov_b32_e32 v25, v15
	v_mov_b32_e32 v24, v15
	v_mov_b32_e32 v23, v15
	v_mov_b32_e32 v22, v15
	v_mov_b32_e32 v21, v15
	v_mov_b32_e32 v20, v15
	v_mov_b32_e32 v19, v15
	v_mov_b32_e32 v18, v15
	v_mov_b32_e32 v17, v15
	v_mov_b32_e32 v16, v15
	s_and_saveexec_b64 s[40:41], s[38:39]
	s_cbranch_execz .LBB0_139
	v_readlane_b32 s38, v254, 10
	v_lshlrev_b64 v[0:1], 12, v[88:89]
	v_readlane_b32 s39, v254, 11
	s_lshl_b32 s92, s50, 1
	v_mov_b32_e32 v85, v161
	v_lshl_add_u64 v[0:1], s[38:39], 0, v[0:1]
	v_lshl_add_u64 v[0:1], v[0:1], 0, s[92:93]
	v_lshl_add_u64 v[0:1], v[0:1], 0, v[84:85]
	global_load_dwordx4 v[48:51], v[0:1], off
	global_load_dwordx4 v[52:55], v[0:1], off offset:32
	global_load_dwordx4 v[56:59], v[0:1], off offset:64
	global_load_dwordx4 v[60:63], v[0:1], off offset:96
	s_and_b32 s38, s3, 0x700
	v_and_b32_e32 v3, 64, v205
	v_add_u32_e32 v85, s38, v111
	s_lshl_b32 s38, s47, 7
	v_xor_b32_e32 v2, 32, v205
	v_add_u32_e32 v3, 64, v3
	s_and_b32 s51, s38, 0x800
	v_cmp_lt_i32_e64 s[38:39], v2, v3
	s_lshl_b32 s94, s42, 6
	s_mov_b32 s95, 0
	v_mov_b32_e32 v135, 0
	v_lshl_add_u64 v[0:1], s[94:95], 1, v[80:81]
	v_cndmask_b32_e64 v2, v205, v2, s[38:39]
	s_lshl_b32 s38, s44, 7
	v_lshlrev_b32_e32 v113, 2, v2
	v_lshl_or_b32 v2, s45, 21, v112
	v_add_u32_e32 v2, v2, v86
	v_mov_b32_e32 v3, v161
	s_and_b32 s38, s38, 0xfffff000
	v_lshl_add_u64 v[90:91], v[0:1], 0, v[2:3]
	v_or_b32_e32 v0, s38, v110
	v_or_b32_e32 v114, s51, v0
	v_mov_b32_e32 v0, 0
	v_lshl_add_u64 v[92:93], v[82:83], 0, s[92:93]
	v_mov_b32_e32 v115, 1.0
	s_mov_b64 s[42:43], 0
	v_mov_b32_e32 v1, v0
	v_mov_b32_e32 v2, v0
	v_mov_b32_e32 v3, v0
	v_mov_b32_e32 v4, v0
	v_mov_b32_e32 v5, v0
	v_mov_b32_e32 v6, v0
	v_mov_b32_e32 v7, v0
	v_mov_b32_e32 v8, v0
	v_mov_b32_e32 v9, v0
	v_mov_b32_e32 v10, v0
	v_mov_b32_e32 v11, v0
	v_mov_b32_e32 v12, v0
	v_mov_b32_e32 v13, v0
	v_mov_b32_e32 v14, v0
	v_mov_b32_e32 v15, v0
	v_mov_b32_e32 v16, v0
	v_mov_b32_e32 v17, v0
	v_mov_b32_e32 v18, v0
	v_mov_b32_e32 v19, v0
	v_mov_b32_e32 v20, v0
	v_mov_b32_e32 v21, v0
	v_mov_b32_e32 v22, v0
	v_mov_b32_e32 v23, v0
	v_mov_b32_e32 v24, v0
	v_mov_b32_e32 v25, v0
	v_mov_b32_e32 v26, v0
	v_mov_b32_e32 v27, v0
	v_mov_b32_e32 v28, v0
	v_mov_b32_e32 v29, v0
	v_mov_b32_e32 v30, v0
	v_mov_b32_e32 v31, v0
	s_branch .LBB0_143

.LBB0_143:
	v_add_u32_e32 v32, v114, v160
	v_ashrrev_i32_e32 v33, 31, v32
	v_lshlrev_b64 v[32:33], 12, v[32:33]
	v_lshl_add_u64 v[72:73], v[92:93], 0, v[32:33]
	global_load_dwordx4 v[32:35], v[72:73], off offset:2048
	global_load_dwordx4 v[64:67], v[72:73], off offset:2080
	global_load_dwordx4 v[68:71], v[72:73], off offset:2112
	global_load_dwordx4 v[94:97], v[72:73], off offset:2144
	v_lshlrev_b32_e32 v134, 6, v160
	s_movk_i32 s38, 0x800
	v_lshl_add_u64 v[76:77], v[134:135], 1, v[90:91]
	s_waitcnt vmcnt(3)
	v_mfma_f32_32x32x16_bf16 v[32:47], v[32:35], v[48:51], 0
	s_waitcnt vmcnt(2)
	v_mfma_f32_32x32x16_bf16 v[32:47], v[64:67], v[52:55], v[32:47]
	global_load_dwordx4 v[72:75], v[76:77], off
	global_load_dwordx4 v[64:67], v[76:77], off offset:1024
	s_waitcnt vmcnt(3)
	v_mfma_f32_32x32x16_bf16 v[32:47], v[68:71], v[56:59], v[32:47]
	v_add_co_u32_e64 v70, s[38:39], s38, v76
	s_nop 1
	v_addc_co_u32_e64 v71, s[38:39], 0, v77, s[38:39]
	global_load_dwordx4 v[76:79], v[70:71], off
	global_load_dwordx4 v[68:71], v[70:71], off offset:1024
	v_cmp_eq_u32_e64 s[38:39], v85, v160
	s_waitcnt vmcnt(4)
	v_mfma_f32_32x32x16_bf16 v[32:47], v[94:97], v[60:63], v[32:47]
	s_nop 11
	v_exp_f32_e32 v32, v32
	v_exp_f32_e32 v33, v33
	v_exp_f32_e32 v34, v34
	v_exp_f32_e32 v35, v35
	v_exp_f32_e32 v94, v36
	v_exp_f32_e32 v95, v37
	v_exp_f32_e32 v38, v38
	v_exp_f32_e32 v39, v39
	v_exp_f32_e32 v40, v40
	v_exp_f32_e32 v41, v41
	v_exp_f32_e32 v42, v42
	v_exp_f32_e32 v43, v43
	v_exp_f32_e32 v96, v44
	v_exp_f32_e32 v97, v45
	v_exp_f32_e32 v46, v46
	v_exp_f32_e32 v47, v47
	v_min_f32_e32 v36, 0x7149f2ca, v32
	v_min_f32_e32 v37, 0x7149f2ca, v33
	v_min_f32_e32 v32, 0x7149f2ca, v34
	v_min_f32_e32 v100, 0x7149f2ca, v35
	v_min_f32_e32 v44, 0x7149f2ca, v94
	v_min_f32_e32 v45, 0x7149f2ca, v95
	v_min_f32_e32 v38, 0x7149f2ca, v38
	v_min_f32_e32 v104, 0x7149f2ca, v39
	v_min_f32_e32 v116, 0x7149f2ca, v40
	v_min_f32_e32 v117, 0x7149f2ca, v41
	v_min_f32_e32 v40, 0x7149f2ca, v42
	v_min_f32_e32 v42, 0x7149f2ca, v43
	v_min_f32_e32 v124, 0x7149f2ca, v96
	v_min_f32_e32 v125, 0x7149f2ca, v97
	v_min_f32_e32 v106, 0x7149f2ca, v46
	v_min_f32_e32 v108, 0x7149f2ca, v47
	v_add_f32_e32 v33, 1.0, v36
	v_add_f32_e32 v34, 1.0, v37
	v_add_f32_e32 v35, 1.0, v32
	v_add_f32_e32 v39, 1.0, v100
	v_add_f32_e32 v41, 1.0, v44
	v_add_f32_e32 v94, 1.0, v45
	v_add_f32_e32 v95, 1.0, v38
	v_add_f32_e32 v98, 1.0, v104
	v_add_f32_e32 v99, 1.0, v116
	v_add_f32_e32 v103, 1.0, v117
	v_add_f32_e32 v107, 1.0, v40
	v_add_f32_e32 v109, 1.0, v42
	v_add_f32_e32 v118, 1.0, v124
	v_add_f32_e32 v119, 1.0, v125
	v_add_f32_e32 v120, 1.0, v106
	v_add_f32_e32 v121, 1.0, v108
	v_rcp_f32_e32 v46, v33
	v_rcp_f32_e32 v47, v34
	v_rcp_f32_e32 v101, v35
	v_rcp_f32_e32 v43, v39
	v_rcp_f32_e32 v96, v41
	v_rcp_f32_e32 v97, v94
	v_rcp_f32_e32 v105, v95
	v_rcp_f32_e32 v41, v98
	v_rcp_f32_e32 v102, v99
	v_rcp_f32_e32 v103, v103
	v_rcp_f32_e32 v107, v107
	v_rcp_f32_e32 v39, v109
	v_rcp_f32_e32 v34, v118
	v_rcp_f32_e32 v35, v119
	v_rcp_f32_e32 v109, v120
	v_rcp_f32_e32 v33, v121
	v_pk_mul_f32 v[98:99], v[36:37], v[46:47]
	v_mul_f32_e32 v123, v32, v101
	v_mul_f32_e32 v122, v100, v43
	v_pk_mul_f32 v[94:95], v[44:45], v[96:97]
	v_mul_f32_e32 v120, v38, v105
	v_mul_f32_e32 v121, v104, v41
	v_pk_mul_f32 v[44:45], v[116:117], v[102:103]
	v_mul_f32_e32 v118, v40, v107
	v_mul_f32_e32 v119, v42, v39
	v_pk_mul_f32 v[36:37], v[124:125], v[34:35]
	v_mul_f32_e32 v116, v106, v109
	v_mul_f32_e32 v117, v108, v33
	s_and_saveexec_b64 s[44:45], s[38:39]
	s_cbranch_execz .LBB0_142
	v_cndmask_b32_e64 v46, 1.0, v46, s[4:5]
	v_cndmask_b32_e64 v47, 1.0, v47, s[6:7]
	v_cndmask_b32_e64 v99, 0, v99, s[6:7]
	v_cndmask_b32_e64 v98, 0, v98, s[4:5]
	v_cndmask_b32_e64 v101, 1.0, v101, s[8:9]
	v_cndmask_b32_e64 v123, 0, v123, s[8:9]
	v_cndmask_b32_e64 v43, 1.0, v43, s[10:11]
	v_cndmask_b32_e64 v122, 0, v122, s[10:11]
	v_cndmask_b32_e64 v96, 1.0, v96, s[14:15]
	v_cndmask_b32_e64 v97, 1.0, v97, s[12:13]
	v_cndmask_b32_e64 v95, 0, v95, s[12:13]
	v_cndmask_b32_e64 v94, 0, v94, s[14:15]
	v_cndmask_b32_e64 v105, 1.0, v105, s[16:17]
	v_cndmask_b32_e64 v120, 0, v120, s[16:17]
	v_cndmask_b32_e64 v41, 1.0, v41, s[18:19]
	v_cndmask_b32_e64 v121, 0, v121, s[18:19]
	v_cndmask_b32_e64 v102, 1.0, v102, s[22:23]
	v_cndmask_b32_e64 v103, 1.0, v103, s[20:21]
	v_cndmask_b32_e64 v45, 0, v45, s[20:21]
	v_cndmask_b32_e64 v44, 0, v44, s[22:23]
	v_cndmask_b32_e64 v107, 1.0, v107, s[24:25]
	v_cndmask_b32_e64 v118, 0, v118, s[24:25]
	v_cndmask_b32_e64 v39, 1.0, v39, s[26:27]
	v_cndmask_b32_e64 v119, 0, v119, s[26:27]
	v_cndmask_b32_e64 v34, 1.0, v34, s[30:31]
	v_cndmask_b32_e64 v35, 1.0, v35, s[28:29]
	v_cndmask_b32_e64 v37, 0, v37, s[28:29]
	v_cndmask_b32_e64 v36, 0, v36, s[30:31]
	v_cndmask_b32_e64 v109, 1.0, v109, s[34:35]
	v_cndmask_b32_e64 v116, 0, v116, s[34:35]
	v_cndmask_b32_e64 v33, 1.0, v33, s[36:37]
	v_cndmask_b32_e64 v117, 0, v117, s[36:37]
	s_branch .LBB0_142
	s_nop 0
	s_nop 0
	s_nop 0
	s_nop 0
	s_nop 0
	s_nop 0
	s_nop 0
	s_nop 0
	s_nop 0
	s_nop 0
	s_nop 0
	s_nop 0
	s_nop 0
	s_nop 0
	s_nop 0
	s_nop 0
	s_nop 0
	s_nop 0
	s_nop 0
	s_nop 0
	s_nop 0
	s_nop 0
	s_nop 0
	s_nop 0
	s_nop 0
	s_nop 0
	s_nop 0
	s_nop 0
	s_nop 0
	s_nop 0
	s_nop 0
	s_nop 0
	s_nop 0
	s_nop 0
	s_nop 0
	s_nop 0
	s_nop 0
	s_nop 0
	s_nop 0
	s_nop 0
	s_nop 0
	s_nop 0
	s_nop 0
	s_nop 0
	s_nop 0
	s_nop 0
	s_nop 0
	s_nop 0
	s_nop 0
	s_nop 0
	s_nop 0
	s_nop 0

.LBB0_265:
	v_lshl_or_b32 v128, s25, 8, v172
	v_ashrrev_i32_e32 v129, 31, v128
	v_lshl_add_u32 v174, s24, 8, v170
	v_lshl_add_u64 v[136:137], v[128:129], 3, s[20:21]
	v_lshrrev_b32_e32 v150, 5, v128
	v_bfe_u32 v151, v128, 4, 1
	v_lshlrev_b32_e32 v151, 10, v151
	v_lshl_or_b32 v150, v150, 12, v151
	v_bfe_u32 v151, v128, 3, 1
	v_lshl_or_b32 v150, v151, 4, v150
	v_and_b32_e32 v151, 15, v174
	v_lshl_or_b32 v150, v151, 5, v150
	v_lshrrev_b32_e32 v151, 6, v174
	v_lshl_or_b32 v150, v151, 21, v150
	v_mov_b32_e32 v151, 0
	v_lshl_add_u64 v[166:167], s[80:81], 0, v[150:151]
	v_add_u32_e32 v150, 0x4000, v150
	v_lshl_add_u64 v[248:249], s[80:81], 0, v[150:151]
	v_add_u32_e32 v150, 0x3fc000, v150
	v_lshl_add_u64 v[250:251], s[80:81], 0, v[150:151]
	v_add_u32_e32 v150, 0x4000, v150
	v_lshl_add_u64 v[150:151], s[80:81], 0, v[150:151]
	global_load_dwordx4 v[128:131], v[136:137], off offset:48
	global_load_dwordx4 v[132:135], v[136:137], off offset:32
	global_load_dwordx4 v[154:157], v[136:137], off offset:16
	global_load_dwordx4 v[176:179], v[136:137], off
	s_mov_b32 s24, 0x35800000
	s_mov_b32 s8, 0x358637bd
	v_mov_b64_e32 v[168:169], s[8:9]
	s_mov_b32 s34, 0x3a800000
	s_mov_b32 s20, 0x45800000
	s_waitcnt vmcnt(0)
	v_ffbh_u32_e32 v138, v179
	v_min_u32_e32 v152, 32, v138
	v_lshlrev_b64 v[138:139], v152, v[178:179]
	v_min_u32_e32 v138, 1, v138
	v_or_b32_e32 v138, v139, v138
	v_cvt_f32_u32_e32 v138, v138
	v_sub_u32_e32 v139, 32, v152
	v_ldexp_f32 v139, v138, v139
	v_ffbh_u32_e32 v138, v177
	v_min_u32_e32 v138, 32, v138
	v_lshlrev_b64 v[152:153], v138, v[176:177]
	v_min_u32_e32 v152, 1, v152
	v_or_b32_e32 v152, v153, v152
	v_cvt_f32_u32_e32 v152, v152
	v_sub_u32_e32 v138, 32, v138
	v_ldexp_f32 v138, v152, v138
	v_pk_mul_f32 v[138:139], v[138:139], s[24:25] op_sel_hi:[1,0]
	s_nop 0
	v_pk_fma_f32 v[138:139], v[138:139], s[34:35], v[168:169] op_sel_hi:[1,0,0]
	s_nop 0
	v_mul_f32_e32 v152, 0x4b800000, v138
	v_cmp_gt_f32_e64 s[8:9], s86, v138
	v_cmp_gt_f32_e32 vcc, s86, v139
	s_nop 0
	v_cndmask_b32_e64 v138, v138, v152, s[8:9]
	v_mul_f32_e32 v152, 0x4b800000, v139
	v_cndmask_b32_e32 v139, v139, v152, vcc
	v_rsq_f32_e32 v138, v138
	v_rsq_f32_e32 v139, v139
	s_nop 0
	v_pk_mul_f32 v[152:153], v[138:139], s[20:21] op_sel_hi:[1,0]
	s_nop 0
	v_cndmask_b32_e64 v152, v138, v152, s[8:9]
	v_ffbh_u32_e32 v138, v157
	v_min_u32_e32 v158, 32, v138
	v_cndmask_b32_e32 v153, v139, v153, vcc
	v_lshlrev_b64 v[138:139], v158, v[156:157]
	v_min_u32_e32 v138, 1, v138
	v_or_b32_e32 v138, v139, v138
	v_cvt_f32_u32_e32 v138, v138
	v_sub_u32_e32 v139, 32, v158
	v_pk_mul_f32 v[124:125], v[124:125], v[152:153]
	v_pk_mul_f32 v[60:61], v[60:61], v[152:153]
	v_ldexp_f32 v139, v138, v139
	v_ffbh_u32_e32 v138, v155
	v_min_u32_e32 v138, 32, v138
	v_lshlrev_b64 v[154:155], v138, v[154:155]
	v_min_u32_e32 v154, 1, v154
	v_or_b32_e32 v154, v155, v154
	v_cvt_f32_u32_e32 v154, v154
	v_sub_u32_e32 v138, 32, v138
	v_ldexp_f32 v138, v154, v138
	v_pk_mul_f32 v[138:139], v[138:139], s[24:25] op_sel_hi:[1,0]
	s_nop 0
	v_pk_fma_f32 v[138:139], v[138:139], s[34:35], v[168:169] op_sel_hi:[1,0,0]
	s_nop 0
	v_mul_f32_e32 v154, 0x4b800000, v138
	v_cmp_gt_f32_e64 s[8:9], s86, v138
	v_cmp_gt_f32_e32 vcc, s86, v139
	s_nop 0
	v_cndmask_b32_e64 v138, v138, v154, s[8:9]
	v_mul_f32_e32 v154, 0x4b800000, v139
	v_cndmask_b32_e32 v139, v139, v154, vcc
	v_rsq_f32_e32 v138, v138
	v_rsq_f32_e32 v139, v139
	s_nop 0
	v_pk_mul_f32 v[154:155], v[138:139], s[20:21] op_sel_hi:[1,0]
	s_nop 0
	v_cndmask_b32_e64 v154, v138, v154, s[8:9]
	v_ffbh_u32_e32 v138, v135
	v_min_u32_e32 v138, 32, v138
	v_lshlrev_b64 v[134:135], v138, v[134:135]
	v_min_u32_e32 v134, 1, v134
	v_or_b32_e32 v134, v135, v134
	v_cvt_f32_u32_e32 v134, v134
	v_sub_u32_e32 v135, 32, v138
	v_cndmask_b32_e32 v155, v139, v155, vcc
	v_pk_mul_f32 v[126:127], v[126:127], v[154:155]
	v_ldexp_f32 v135, v134, v135
	v_ffbh_u32_e32 v134, v133
	v_min_u32_e32 v134, 32, v134
	v_lshlrev_b64 v[132:133], v134, v[132:133]
	v_min_u32_e32 v132, 1, v132
	v_or_b32_e32 v132, v133, v132
	v_cvt_f32_u32_e32 v132, v132
	v_sub_u32_e32 v133, 32, v134
	v_pk_mul_f32 v[62:63], v[62:63], v[154:155]
	v_ldexp_f32 v134, v132, v133
	v_pk_mul_f32 v[132:133], v[134:135], s[24:25] op_sel_hi:[1,0]
	s_nop 0
	v_pk_fma_f32 v[132:133], v[132:133], s[34:35], v[168:169] op_sel_hi:[1,0,0]
	s_nop 0
	v_mul_f32_e32 v134, 0x4b800000, v132
	v_cmp_gt_f32_e64 s[8:9], s86, v132
	v_cmp_gt_f32_e32 vcc, s86, v133
	s_nop 0
	v_cndmask_b32_e64 v132, v132, v134, s[8:9]
	v_mul_f32_e32 v134, 0x4b800000, v133
	v_cndmask_b32_e32 v133, v133, v134, vcc
	v_rsq_f32_e32 v132, v132
	v_rsq_f32_e32 v133, v133
	s_nop 0
	v_pk_mul_f32 v[134:135], v[132:133], s[20:21] op_sel_hi:[1,0]
	s_nop 0
	v_cndmask_b32_e32 v157, v133, v135, vcc
	v_cndmask_b32_e64 v156, v132, v134, s[8:9]
	v_pk_mul_f32 v[132:133], v[120:121], v[156:157]
	v_ffbh_u32_e32 v120, v131
	v_min_u32_e32 v134, 32, v120
	v_lshlrev_b64 v[120:121], v134, v[130:131]
	v_min_u32_e32 v120, 1, v120
	v_or_b32_e32 v120, v121, v120
	v_cvt_f32_u32_e32 v120, v120
	v_sub_u32_e32 v121, 32, v134
	v_pk_mul_f32 v[108:109], v[108:109], v[156:157]
	v_pk_mul_f32 v[92:93], v[92:93], v[156:157]
	v_ldexp_f32 v121, v120, v121
	v_ffbh_u32_e32 v120, v129
	v_min_u32_e32 v120, 32, v120
	v_lshlrev_b64 v[128:129], v120, v[128:129]
	v_min_u32_e32 v128, 1, v128
	v_or_b32_e32 v128, v129, v128
	v_cvt_f32_u32_e32 v128, v128
	v_sub_u32_e32 v120, 32, v120
	v_cvt_pk_bf16_f32 v108, v108, v109
	v_pk_mul_f32 v[76:77], v[76:77], v[156:157]
	v_ldexp_f32 v120, v128, v120
	v_pk_mul_f32 v[120:121], v[120:121], s[24:25] op_sel_hi:[1,0]
	v_pk_mul_f32 v[44:45], v[44:45], v[156:157]
	v_pk_fma_f32 v[120:121], v[120:121], s[34:35], v[168:169] op_sel_hi:[1,0,0]
	v_pk_mul_f32 v[28:29], v[28:29], v[156:157]
	v_mul_f32_e32 v128, 0x4b800000, v120
	v_cmp_gt_f32_e64 s[8:9], s86, v120
	v_cmp_gt_f32_e32 vcc, s86, v121
	v_pk_mul_f32 v[12:13], v[12:13], v[156:157]
	v_cndmask_b32_e64 v120, v120, v128, s[8:9]
	v_mul_f32_e32 v128, 0x4b800000, v121
	v_cndmask_b32_e32 v121, v121, v128, vcc
	v_rsq_f32_e32 v120, v120
	v_rsq_f32_e32 v121, v121
	s_nop 0
	v_pk_mul_f32 v[128:129], v[120:121], s[20:21] op_sel_hi:[1,0]
	s_nop 0
	v_cndmask_b32_e32 v159, v121, v129, vcc
	v_cndmask_b32_e64 v158, v120, v128, s[8:9]
	v_pk_mul_f32 v[128:129], v[122:123], v[158:159]
	v_cvt_pk_bf16_f32 v120, v124, v125
	v_cvt_pk_bf16_f32 v121, v126, v127
	v_cvt_pk_bf16_f32 v122, v132, v133
	v_cvt_pk_bf16_f32 v123, v128, v129
	global_load_dwordx4 v[124:127], v[136:137], off offset:1072
	global_load_dwordx4 v[128:131], v[136:137], off offset:1056
	global_load_dwordx4 v[132:135], v[136:137], off offset:1040
	s_nop 0
	global_load_dwordx4 v[136:139], v[136:137], off offset:1024
	v_pk_mul_f32 v[110:111], v[110:111], v[158:159]
	global_store_dwordx4 v[166:167], v[120:123], off
	v_cvt_pk_bf16_f32 v109, v110, v111
	v_pk_mul_f32 v[94:95], v[94:95], v[158:159]
	v_pk_mul_f32 v[78:79], v[78:79], v[158:159]
	v_pk_mul_f32 v[46:47], v[46:47], v[158:159]
	v_pk_mul_f32 v[30:31], v[30:31], v[158:159]
	v_pk_mul_f32 v[14:15], v[14:15], v[158:159]
	s_waitcnt vmcnt(0)
	v_ffbh_u32_e32 v176, v139
	v_min_u32_e32 v176, 32, v176
	v_lshlrev_b64 v[138:139], v176, v[138:139]
	v_min_u32_e32 v138, 1, v138
	v_or_b32_e32 v138, v139, v138
	v_cvt_f32_u32_e32 v138, v138
	v_sub_u32_e32 v139, 32, v176
	v_ldexp_f32 v139, v138, v139
	v_ffbh_u32_e32 v138, v137
	v_min_u32_e32 v138, 32, v138
	v_lshlrev_b64 v[136:137], v138, v[136:137]
	v_min_u32_e32 v136, 1, v136
	v_or_b32_e32 v136, v137, v136
	v_cvt_f32_u32_e32 v136, v136
	v_sub_u32_e32 v137, 32, v138
	v_ldexp_f32 v138, v136, v137
	v_pk_mul_f32 v[136:137], v[138:139], s[24:25] op_sel_hi:[1,0]
	s_nop 0
	v_pk_fma_f32 v[136:137], v[136:137], s[34:35], v[168:169] op_sel_hi:[1,0,0]
	s_nop 0
	v_mul_f32_e32 v138, 0x4b800000, v136
	v_cmp_gt_f32_e64 s[8:9], s86, v136
	v_cmp_gt_f32_e32 vcc, s86, v137
	s_nop 0
	v_cndmask_b32_e64 v136, v136, v138, s[8:9]
	v_mul_f32_e32 v138, 0x4b800000, v137
	v_cndmask_b32_e32 v137, v137, v138, vcc
	v_rsq_f32_e32 v136, v136
	v_rsq_f32_e32 v137, v137
	s_nop 0
	v_pk_mul_f32 v[138:139], v[136:137], s[20:21] op_sel_hi:[1,0]
	s_nop 0
	v_cndmask_b32_e32 v137, v137, v139, vcc
	v_cndmask_b32_e64 v136, v136, v138, s[8:9]
	v_pk_mul_f32 v[138:139], v[116:117], v[136:137]
	v_ffbh_u32_e32 v116, v135
	v_min_u32_e32 v176, 32, v116
	v_lshlrev_b64 v[116:117], v176, v[134:135]
	v_min_u32_e32 v116, 1, v116
	v_or_b32_e32 v116, v117, v116
	v_cvt_f32_u32_e32 v116, v116
	v_sub_u32_e32 v117, 32, v176
	v_cvt_pk_bf16_f32 v120, v138, v139
	v_pk_mul_f32 v[96:97], v[96:97], v[136:137]
	v_ldexp_f32 v117, v116, v117
	v_ffbh_u32_e32 v116, v133
	v_min_u32_e32 v116, 32, v116
	v_lshlrev_b64 v[132:133], v116, v[132:133]
	v_min_u32_e32 v132, 1, v132
	v_or_b32_e32 v132, v133, v132
	v_cvt_f32_u32_e32 v132, v132
	v_sub_u32_e32 v116, 32, v116
	v_pk_mul_f32 v[80:81], v[80:81], v[136:137]
	v_pk_mul_f32 v[68:69], v[68:69], v[136:137]
	v_ldexp_f32 v116, v132, v116
	v_pk_mul_f32 v[116:117], v[116:117], s[24:25] op_sel_hi:[1,0]
	v_pk_mul_f32 v[48:49], v[48:49], v[136:137]
	v_pk_fma_f32 v[116:117], v[116:117], s[34:35], v[168:169] op_sel_hi:[1,0,0]
	v_pk_mul_f32 v[32:33], v[32:33], v[136:137]
	v_mul_f32_e32 v132, 0x4b800000, v116
	v_cmp_gt_f32_e64 s[8:9], s86, v116
	v_cmp_gt_f32_e32 vcc, s86, v117
	v_pk_mul_f32 v[16:17], v[16:17], v[136:137]
	v_cndmask_b32_e64 v116, v116, v132, s[8:9]
	v_mul_f32_e32 v132, 0x4b800000, v117
	v_cndmask_b32_e32 v117, v117, v132, vcc
	v_rsq_f32_e32 v116, v116
	v_rsq_f32_e32 v117, v117
	v_pk_mul_f32 v[4:5], v[4:5], v[136:137]
	v_pk_mul_f32 v[132:133], v[116:117], s[20:21] op_sel_hi:[1,0]
	s_nop 0
	v_cndmask_b32_e32 v117, v117, v133, vcc
	v_cndmask_b32_e64 v116, v116, v132, s[8:9]
	v_pk_mul_f32 v[132:133], v[118:119], v[116:117]
	v_ffbh_u32_e32 v118, v131
	v_min_u32_e32 v134, 32, v118
	v_lshlrev_b64 v[118:119], v134, v[130:131]
	v_min_u32_e32 v118, 1, v118
	v_or_b32_e32 v118, v119, v118
	v_cvt_f32_u32_e32 v118, v118
	v_sub_u32_e32 v119, 32, v134
	v_cvt_pk_bf16_f32 v121, v132, v133
	v_pk_mul_f32 v[98:99], v[98:99], v[116:117]
	v_ldexp_f32 v119, v118, v119
	v_ffbh_u32_e32 v118, v129
	v_min_u32_e32 v118, 32, v118
	v_lshlrev_b64 v[128:129], v118, v[128:129]
	v_min_u32_e32 v128, 1, v128
	v_or_b32_e32 v128, v129, v128
	v_cvt_f32_u32_e32 v128, v128
	v_sub_u32_e32 v118, 32, v118
	v_pk_mul_f32 v[82:83], v[82:83], v[116:117]
	v_pk_mul_f32 v[70:71], v[70:71], v[116:117]
	v_ldexp_f32 v118, v128, v118
	v_pk_mul_f32 v[118:119], v[118:119], s[24:25] op_sel_hi:[1,0]
	v_pk_mul_f32 v[50:51], v[50:51], v[116:117]
	v_pk_fma_f32 v[118:119], v[118:119], s[34:35], v[168:169] op_sel_hi:[1,0,0]
	v_pk_mul_f32 v[34:35], v[34:35], v[116:117]
	v_mul_f32_e32 v128, 0x4b800000, v118
	v_cmp_gt_f32_e64 s[8:9], s86, v118
	v_cmp_gt_f32_e32 vcc, s86, v119
	v_pk_mul_f32 v[18:19], v[18:19], v[116:117]
	v_cndmask_b32_e64 v118, v118, v128, s[8:9]
	v_mul_f32_e32 v128, 0x4b800000, v119
	v_cndmask_b32_e32 v119, v119, v128, vcc
	v_rsq_f32_e32 v118, v118
	v_rsq_f32_e32 v119, v119
	v_pk_mul_f32 v[6:7], v[6:7], v[116:117]
	v_pk_mul_f32 v[128:129], v[118:119], s[20:21] op_sel_hi:[1,0]
	s_nop 0
	v_cndmask_b32_e32 v119, v119, v129, vcc
	v_cndmask_b32_e64 v118, v118, v128, s[8:9]
	v_pk_mul_f32 v[128:129], v[104:105], v[118:119]
	v_ffbh_u32_e32 v104, v127
	v_min_u32_e32 v130, 32, v104
	v_lshlrev_b64 v[104:105], v130, v[126:127]
	v_min_u32_e32 v104, 1, v104
	v_or_b32_e32 v104, v105, v104
	v_cvt_f32_u32_e32 v104, v104
	v_sub_u32_e32 v105, 32, v130
	v_cvt_pk_bf16_f32 v122, v128, v129
	v_ldexp_f32 v105, v104, v105
	v_ffbh_u32_e32 v104, v125
	v_min_u32_e32 v104, 32, v104
	v_lshlrev_b64 v[124:125], v104, v[124:125]
	v_min_u32_e32 v124, 1, v124
	v_or_b32_e32 v124, v125, v124
	v_cvt_f32_u32_e32 v124, v124
	v_sub_u32_e32 v104, 32, v104
	v_ldexp_f32 v104, v124, v104
	v_pk_mul_f32 v[104:105], v[104:105], s[24:25] op_sel_hi:[1,0]
	s_mov_b32 s25, s84
	v_pk_fma_f32 v[104:105], v[104:105], s[34:35], v[168:169] op_sel_hi:[1,0,0]
	s_mov_b32 s24, s85
	v_mul_f32_e32 v124, 0x4b800000, v104
	v_cmp_gt_f32_e64 s[8:9], s86, v104
	v_cmp_gt_f32_e32 vcc, s86, v105
	s_nop 0
	v_cndmask_b32_e64 v104, v104, v124, s[8:9]
	v_mul_f32_e32 v124, 0x4b800000, v105
	v_cndmask_b32_e32 v105, v105, v124, vcc
	v_rsq_f32_e32 v104, v104
	v_rsq_f32_e32 v105, v105
	s_nop 0
	v_pk_mul_f32 v[124:125], v[104:105], s[20:21] op_sel_hi:[1,0]
	s_nop 0
	v_cndmask_b32_e32 v105, v105, v125, vcc
	v_cndmask_b32_e64 v104, v104, v124, s[8:9]
	v_pk_mul_f32 v[106:107], v[106:107], v[104:105]
	s_and_b64 vcc, exec, s[6:7]
	v_cvt_pk_bf16_f32 v123, v106, v107
	global_store_dwordx4 v[248:249], v[120:123], off
	s_mov_b64 s[20:21], s[10:11]
	s_nop 0
	v_pk_mul_f32 v[106:107], v[112:113], v[152:153]
	v_pk_mul_f32 v[112:113], v[114:115], v[154:155]
	v_cvt_pk_bf16_f32 v106, v106, v107
	v_cvt_pk_bf16_f32 v107, v112, v113
	global_store_dwordx4 v[166:167], v[106:109], off offset:512
	s_nop 1
	v_pk_mul_f32 v[106:107], v[88:89], v[118:119]
	v_pk_mul_f32 v[108:109], v[90:91], v[104:105]
	v_cvt_pk_bf16_f32 v88, v96, v97
	v_cvt_pk_bf16_f32 v89, v98, v99
	v_cvt_pk_bf16_f32 v90, v106, v107
	v_cvt_pk_bf16_f32 v91, v108, v109
	global_store_dwordx4 v[248:249], v[88:91], off offset:512
	s_nop 1
	v_pk_mul_f32 v[88:89], v[100:101], v[152:153]
	v_pk_mul_f32 v[90:91], v[102:103], v[154:155]
	v_cvt_pk_bf16_f32 v88, v88, v89
	v_cvt_pk_bf16_f32 v89, v90, v91
	v_cvt_pk_bf16_f32 v90, v92, v93
	v_cvt_pk_bf16_f32 v91, v94, v95
	global_store_dwordx4 v[166:167], v[88:91], off offset:2048
	s_nop 1
	v_pk_mul_f32 v[88:89], v[72:73], v[118:119]
	v_pk_mul_f32 v[90:91], v[74:75], v[104:105]
	v_cvt_pk_bf16_f32 v72, v80, v81
	v_cvt_pk_bf16_f32 v73, v82, v83
	v_cvt_pk_bf16_f32 v74, v88, v89
	v_cvt_pk_bf16_f32 v75, v90, v91
	global_store_dwordx4 v[248:249], v[72:75], off offset:2048
	s_nop 1
	v_pk_mul_f32 v[72:73], v[84:85], v[152:153]
	v_pk_mul_f32 v[74:75], v[86:87], v[154:155]
	v_cvt_pk_bf16_f32 v72, v72, v73
	v_cvt_pk_bf16_f32 v73, v74, v75
	v_cvt_pk_bf16_f32 v74, v76, v77
	v_cvt_pk_bf16_f32 v75, v78, v79
	global_store_dwordx4 v[166:167], v[72:75], off offset:2560
	s_nop 1
	v_pk_mul_f32 v[72:73], v[64:65], v[118:119]
	v_pk_mul_f32 v[74:75], v[66:67], v[104:105]
	v_cvt_pk_bf16_f32 v64, v68, v69
	v_cvt_pk_bf16_f32 v65, v70, v71
	v_cvt_pk_bf16_f32 v66, v72, v73
	v_cvt_pk_bf16_f32 v67, v74, v75
	global_store_dwordx4 v[248:249], v[64:67], off offset:2560
	v_pk_mul_f32 v[68:69], v[58:59], v[158:159]
	s_nop 0
	v_pk_mul_f32 v[66:67], v[56:57], v[156:157]
	v_cvt_pk_bf16_f32 v56, v60, v61
	v_cvt_pk_bf16_f32 v57, v62, v63
	v_cvt_pk_bf16_f32 v58, v66, v67
	v_cvt_pk_bf16_f32 v59, v68, v69
	global_store_dwordx4 v[250:251], v[56:59], off
	s_nop 1
	v_pk_mul_f32 v[56:57], v[40:41], v[118:119]
	v_pk_mul_f32 v[58:59], v[42:43], v[104:105]
	v_cvt_pk_bf16_f32 v40, v48, v49
	v_cvt_pk_bf16_f32 v41, v50, v51
	v_cvt_pk_bf16_f32 v42, v56, v57
	v_cvt_pk_bf16_f32 v43, v58, v59
	global_store_dwordx4 v[150:151], v[40:43], off
	s_nop 1
	v_pk_mul_f32 v[40:41], v[52:53], v[152:153]
	v_pk_mul_f32 v[42:43], v[54:55], v[154:155]
	v_cvt_pk_bf16_f32 v40, v40, v41
	v_cvt_pk_bf16_f32 v41, v42, v43
	v_cvt_pk_bf16_f32 v42, v44, v45
	v_cvt_pk_bf16_f32 v43, v46, v47
	global_store_dwordx4 v[250:251], v[40:43], off offset:512
	s_nop 1
	v_pk_mul_f32 v[40:41], v[24:25], v[118:119]
	v_pk_mul_f32 v[42:43], v[26:27], v[104:105]
	v_cvt_pk_bf16_f32 v24, v32, v33
	v_cvt_pk_bf16_f32 v25, v34, v35
	v_cvt_pk_bf16_f32 v26, v40, v41
	v_cvt_pk_bf16_f32 v27, v42, v43
	global_store_dwordx4 v[150:151], v[24:27], off offset:512
	s_nop 1
	v_pk_mul_f32 v[24:25], v[36:37], v[152:153]
	v_pk_mul_f32 v[26:27], v[38:39], v[154:155]
	v_cvt_pk_bf16_f32 v24, v24, v25
	v_cvt_pk_bf16_f32 v25, v26, v27
	v_cvt_pk_bf16_f32 v26, v28, v29
	v_cvt_pk_bf16_f32 v27, v30, v31
	global_store_dwordx4 v[250:251], v[24:27], off offset:2048
	s_nop 1
	v_pk_mul_f32 v[24:25], v[8:9], v[118:119]
	v_pk_mul_f32 v[26:27], v[10:11], v[104:105]
	v_cvt_pk_bf16_f32 v8, v16, v17
	v_cvt_pk_bf16_f32 v9, v18, v19
	v_cvt_pk_bf16_f32 v10, v24, v25
	v_cvt_pk_bf16_f32 v11, v26, v27
	global_store_dwordx4 v[150:151], v[8:11], off offset:2048
	s_nop 1
	v_pk_mul_f32 v[8:9], v[20:21], v[152:153]
	v_pk_mul_f32 v[10:11], v[22:23], v[154:155]
	v_cvt_pk_bf16_f32 v8, v8, v9
	v_cvt_pk_bf16_f32 v9, v10, v11
	v_cvt_pk_bf16_f32 v10, v12, v13
	v_cvt_pk_bf16_f32 v11, v14, v15
	global_store_dwordx4 v[250:251], v[8:11], off offset:2560
	s_mov_b64 s[30:31], s[76:77]
	s_nop 0
	v_pk_mul_f32 v[8:9], v[0:1], v[118:119]
	v_pk_mul_f32 v[10:11], v[2:3], v[104:105]
	v_cvt_pk_bf16_f32 v0, v4, v5
	v_cvt_pk_bf16_f32 v1, v6, v7
	v_cvt_pk_bf16_f32 v2, v8, v9
	v_cvt_pk_bf16_f32 v3, v10, v11
	global_store_dwordx4 v[150:151], v[0:3], off offset:2560
	s_cbranch_vccnz .LBB0_318
